# early barrier with the priority raise folded into the mid-block toggle (single s_setprio 3 replaces setprio 0/1 pair; bare s_barrier before the 4-MFMA tail)
# baseline (speedup 1.0000x reference)
.LBB0_115:
	ds_read_b128 v[148:151], v154
	ds_read_b128 v[158:161], v154 offset:1024
	ds_read_b128 v[162:165], v154 offset:2048
	ds_read_b128 v[166:169], v154 offset:3072
	ds_read_b128 v[170:173], v155
	ds_read_b128 v[174:177], v155 offset:1024
	ds_read_b128 v[178:181], v155 offset:2048
	ds_read_b128 v[182:185], v155 offset:3072
	s_add_u32 s46, s44, 0xfff00080
	s_addc_u32 s47, s45, -1
	s_cmp_eq_u32 s69, 60
	s_cselect_b32 s49, s35, s47
	s_cselect_b32 s48, s43, s46
	s_cselect_b32 s47, s37, s68
	s_cselect_b32 s46, s66, s67
	v_lshl_add_u64 v[218:219], s[44:45], 0, v[140:141]
	s_add_i32 m0, s54, 0xc000
	ds_read_b128 v[186:189], v156
	ds_read_b128 v[190:193], v156 offset:1024
	ds_read_b128 v[194:197], v156 offset:2048
	ds_read_b128 v[198:201], v156 offset:3072
	ds_read_b128 v[202:205], v156 offset:4096
	ds_read_b128 v[206:209], v156 offset:5120
	ds_read_b128 v[210:213], v156 offset:6144
	ds_read_b128 v[214:217], v156 offset:7168
	global_load_lds_dwordx4 v[218:219], off
	v_lshl_add_u64 v[218:219], s[44:45], 0, v[142:143]
	s_add_i32 m0, s54, 0xe000
	s_nop 0
	global_load_lds_dwordx4 v[218:219], off
	s_waitcnt vmcnt(8)
	s_waitcnt lgkmcnt(0)
	s_barrier
	s_setprio 1
	s_waitcnt lgkmcnt(0)
	v_mfma_f32_16x16x32_bf16 v[126:129], v[148:151], v[186:189], v[126:129]
	v_mfma_f32_16x16x32_bf16 v[122:125], v[162:165], v[186:189], v[122:125]
	v_mfma_f32_16x16x32_bf16 v[118:121], v[148:151], v[194:197], v[118:121]
	v_mfma_f32_16x16x32_bf16 v[110:113], v[162:165], v[194:197], v[110:113]
	v_mfma_f32_16x16x32_bf16 v[102:105], v[148:151], v[202:205], v[102:105]
	v_mfma_f32_16x16x32_bf16 v[94:97], v[162:165], v[202:205], v[94:97]
	v_mfma_f32_16x16x32_bf16 v[86:89], v[148:151], v[210:213], v[86:89]
	v_mfma_f32_16x16x32_bf16 v[78:81], v[162:165], v[210:213], v[78:81]
	v_mfma_f32_16x16x32_bf16 v[126:129], v[158:161], v[190:193], v[126:129]
	v_mfma_f32_16x16x32_bf16 v[122:125], v[166:169], v[190:193], v[122:125]
	v_mfma_f32_16x16x32_bf16 v[118:121], v[158:161], v[198:201], v[118:121]
	v_mfma_f32_16x16x32_bf16 v[110:113], v[166:169], v[198:201], v[110:113]
	v_mfma_f32_16x16x32_bf16 v[102:105], v[158:161], v[206:209], v[102:105]
	v_mfma_f32_16x16x32_bf16 v[94:97], v[166:169], v[206:209], v[94:97]
	v_mfma_f32_16x16x32_bf16 v[86:89], v[158:161], v[214:217], v[86:89]
	v_mfma_f32_16x16x32_bf16 v[78:81], v[166:169], v[214:217], v[78:81]
	s_setprio 3
	v_mfma_f32_16x16x32_bf16 v[114:117], v[170:173], v[186:189], v[114:117]
	v_mfma_f32_16x16x32_bf16 v[106:109], v[178:181], v[186:189], v[106:109]
	v_mfma_f32_16x16x32_bf16 v[98:101], v[170:173], v[194:197], v[98:101]
	v_mfma_f32_16x16x32_bf16 v[90:93], v[178:181], v[194:197], v[90:93]
	v_mfma_f32_16x16x32_bf16 v[82:85], v[170:173], v[202:205], v[82:85]
	v_mfma_f32_16x16x32_bf16 v[74:77], v[178:181], v[202:205], v[74:77]
	v_mfma_f32_16x16x32_bf16 v[70:73], v[170:173], v[210:213], v[70:73]
	v_mfma_f32_16x16x32_bf16 v[66:69], v[178:181], v[210:213], v[66:69]
	v_mfma_f32_16x16x32_bf16 v[114:117], v[174:177], v[190:193], v[114:117]
	v_mfma_f32_16x16x32_bf16 v[106:109], v[182:185], v[190:193], v[106:109]
	v_mfma_f32_16x16x32_bf16 v[98:101], v[174:177], v[198:201], v[98:101]
	v_mfma_f32_16x16x32_bf16 v[90:93], v[182:185], v[198:201], v[90:93]
	s_barrier
	v_mfma_f32_16x16x32_bf16 v[82:85], v[174:177], v[206:209], v[82:85]
	v_mfma_f32_16x16x32_bf16 v[74:77], v[182:185], v[206:209], v[74:77]
	v_mfma_f32_16x16x32_bf16 v[70:73], v[174:177], v[214:217], v[70:73]
	v_mfma_f32_16x16x32_bf16 v[66:69], v[182:185], v[214:217], v[66:69]
	s_setprio 0
	s_add_i32 s70, s64, s51
	v_lshl_add_u64 v[218:219], s[46:47], 0, v[134:135]
	s_mov_b32 m0, s70
	ds_read_b128 v[186:189], v156 offset:16384
	ds_read_b128 v[190:193], v156 offset:17408
	ds_read_b128 v[194:197], v156 offset:18432
	ds_read_b128 v[198:201], v156 offset:19456
	ds_read_b128 v[202:205], v156 offset:20480
	ds_read_b128 v[206:209], v156 offset:21504
	ds_read_b128 v[210:213], v156 offset:22528
	ds_read_b128 v[214:217], v156 offset:23552
	global_load_lds_dwordx4 v[218:219], off
	s_add_i32 m0, s70, 0x2000
	s_add_u32 s70, s46, 0x100000
	v_lshl_add_u64 v[220:221], s[46:47], 0, v[130:131]
	s_addc_u32 s71, s47, 0
	s_add_i32 s72, s65, s51
	global_load_lds_dwordx4 v[220:221], off
	v_lshl_add_u64 v[222:223], s[70:71], 0, v[134:135]
	s_mov_b32 m0, s72
	v_lshl_add_u64 v[224:225], s[48:49], 0, v[132:133]
	global_load_lds_dwordx4 v[222:223], off
	v_lshl_add_u64 v[222:223], s[70:71], 0, v[130:131]
	s_add_i32 m0, s72, 0x2000
	s_nop 0
	global_load_lds_dwordx4 v[222:223], off
	v_lshl_add_u64 v[222:223], s[48:49], 0, v[136:137]
	s_mov_b32 m0, s54
	s_nop 0
	global_load_lds_dwordx4 v[222:223], off
	s_mov_b32 m0, s55
	s_nop 0
	global_load_lds_dwordx4 v[224:225], off
	s_waitcnt vmcnt(8)
	s_waitcnt lgkmcnt(0)
	s_barrier
	s_setprio 1
	s_waitcnt lgkmcnt(0)
	v_mfma_f32_16x16x32_bf16 v[62:65], v[148:151], v[186:189], v[62:65]
	v_mfma_f32_16x16x32_bf16 v[58:61], v[162:165], v[186:189], v[58:61]
	v_mfma_f32_16x16x32_bf16 v[54:57], v[148:151], v[194:197], v[54:57]
	v_mfma_f32_16x16x32_bf16 v[46:49], v[162:165], v[194:197], v[46:49]
	v_mfma_f32_16x16x32_bf16 v[38:41], v[148:151], v[202:205], v[38:41]
	v_mfma_f32_16x16x32_bf16 v[30:33], v[162:165], v[202:205], v[30:33]
	v_mfma_f32_16x16x32_bf16 v[22:25], v[148:151], v[210:213], v[22:25]
	v_mfma_f32_16x16x32_bf16 v[14:17], v[162:165], v[210:213], v[14:17]
	v_mfma_f32_16x16x32_bf16 v[62:65], v[158:161], v[190:193], v[62:65]
	v_mfma_f32_16x16x32_bf16 v[58:61], v[166:169], v[190:193], v[58:61]
	v_mfma_f32_16x16x32_bf16 v[54:57], v[158:161], v[198:201], v[54:57]
	v_mfma_f32_16x16x32_bf16 v[46:49], v[166:169], v[198:201], v[46:49]
	v_mfma_f32_16x16x32_bf16 v[38:41], v[158:161], v[206:209], v[38:41]
	v_mfma_f32_16x16x32_bf16 v[30:33], v[166:169], v[206:209], v[30:33]
	v_mfma_f32_16x16x32_bf16 v[22:25], v[158:161], v[214:217], v[22:25]
	v_mfma_f32_16x16x32_bf16 v[14:17], v[166:169], v[214:217], v[14:17]
	s_setprio 3
	v_mfma_f32_16x16x32_bf16 v[50:53], v[170:173], v[186:189], v[50:53]
	v_mfma_f32_16x16x32_bf16 v[42:45], v[178:181], v[186:189], v[42:45]
	v_mfma_f32_16x16x32_bf16 v[34:37], v[170:173], v[194:197], v[34:37]
	v_mfma_f32_16x16x32_bf16 v[26:29], v[178:181], v[194:197], v[26:29]
	v_mfma_f32_16x16x32_bf16 v[18:21], v[170:173], v[202:205], v[18:21]
	v_mfma_f32_16x16x32_bf16 v[10:13], v[178:181], v[202:205], v[10:13]
	v_mfma_f32_16x16x32_bf16 v[6:9], v[170:173], v[210:213], v[6:9]
	v_mfma_f32_16x16x32_bf16 v[2:5], v[178:181], v[210:213], v[2:5]
	v_mfma_f32_16x16x32_bf16 v[50:53], v[174:177], v[190:193], v[50:53]
	v_mfma_f32_16x16x32_bf16 v[42:45], v[182:185], v[190:193], v[42:45]
	v_mfma_f32_16x16x32_bf16 v[34:37], v[174:177], v[198:201], v[34:37]
	v_mfma_f32_16x16x32_bf16 v[26:29], v[182:185], v[198:201], v[26:29]
	s_barrier
	v_mfma_f32_16x16x32_bf16 v[18:21], v[174:177], v[206:209], v[18:21]
	v_mfma_f32_16x16x32_bf16 v[10:13], v[182:185], v[206:209], v[10:13]
	v_mfma_f32_16x16x32_bf16 v[6:9], v[174:177], v[214:217], v[6:9]
	v_mfma_f32_16x16x32_bf16 v[2:5], v[182:185], v[214:217], v[2:5]
	s_setprio 0
	s_add_i32 s70, 0, 0x18000
	v_add_u32_e32 v138, s70, v152
	s_add_i32 s71, 0, 0x1c000
	ds_read_b128 v[148:151], v138
	ds_read_b128 v[158:161], v138 offset:1024
	ds_read_b128 v[162:165], v138 offset:2048
	ds_read_b128 v[166:169], v138 offset:3072
	v_add_u32_e32 v138, s71, v152
	ds_read_b128 v[170:173], v138
	ds_read_b128 v[174:177], v138 offset:1024
	ds_read_b128 v[178:181], v138 offset:2048
	ds_read_b128 v[182:185], v138 offset:3072
	s_add_u32 s48, s48, 0x100000
	s_addc_u32 s49, s49, 0
	s_mov_b32 m0, s56
	v_lshl_add_u64 v[226:227], s[48:49], 0, v[136:137]
	ds_read_b128 v[186:189], v156 offset:32768
	ds_read_b128 v[190:193], v156 offset:33792
	ds_read_b128 v[194:197], v156 offset:34816
	ds_read_b128 v[198:201], v156 offset:35840
	ds_read_b128 v[202:205], v156 offset:36864
	ds_read_b128 v[206:209], v156 offset:37888
	ds_read_b128 v[210:213], v156 offset:38912
	ds_read_b128 v[214:217], v156 offset:39936
	global_load_lds_dwordx4 v[226:227], off
	v_lshl_add_u64 v[226:227], s[48:49], 0, v[132:133]
	s_mov_b32 m0, s57
	s_nop 0
	global_load_lds_dwordx4 v[226:227], off
	s_waitcnt vmcnt(8)
	s_waitcnt lgkmcnt(0)
	s_barrier
	s_setprio 1
	s_waitcnt lgkmcnt(0)
	v_mfma_f32_16x16x32_bf16 v[126:129], v[148:151], v[186:189], v[126:129]
	v_mfma_f32_16x16x32_bf16 v[122:125], v[162:165], v[186:189], v[122:125]
	v_mfma_f32_16x16x32_bf16 v[118:121], v[148:151], v[194:197], v[118:121]
	v_mfma_f32_16x16x32_bf16 v[110:113], v[162:165], v[194:197], v[110:113]
	v_mfma_f32_16x16x32_bf16 v[102:105], v[148:151], v[202:205], v[102:105]
	v_mfma_f32_16x16x32_bf16 v[94:97], v[162:165], v[202:205], v[94:97]
	v_mfma_f32_16x16x32_bf16 v[86:89], v[148:151], v[210:213], v[86:89]
	v_mfma_f32_16x16x32_bf16 v[78:81], v[162:165], v[210:213], v[78:81]
	v_mfma_f32_16x16x32_bf16 v[126:129], v[158:161], v[190:193], v[126:129]
	v_mfma_f32_16x16x32_bf16 v[122:125], v[166:169], v[190:193], v[122:125]
	v_mfma_f32_16x16x32_bf16 v[118:121], v[158:161], v[198:201], v[118:121]
	v_mfma_f32_16x16x32_bf16 v[110:113], v[166:169], v[198:201], v[110:113]
	v_mfma_f32_16x16x32_bf16 v[102:105], v[158:161], v[206:209], v[102:105]
	v_mfma_f32_16x16x32_bf16 v[94:97], v[166:169], v[206:209], v[94:97]
	v_mfma_f32_16x16x32_bf16 v[86:89], v[158:161], v[214:217], v[86:89]
	v_mfma_f32_16x16x32_bf16 v[78:81], v[166:169], v[214:217], v[78:81]
	s_setprio 3
	v_mfma_f32_16x16x32_bf16 v[114:117], v[170:173], v[186:189], v[114:117]
	v_mfma_f32_16x16x32_bf16 v[106:109], v[178:181], v[186:189], v[106:109]
	v_mfma_f32_16x16x32_bf16 v[98:101], v[170:173], v[194:197], v[98:101]
	v_mfma_f32_16x16x32_bf16 v[90:93], v[178:181], v[194:197], v[90:93]
	v_mfma_f32_16x16x32_bf16 v[82:85], v[170:173], v[202:205], v[82:85]
	v_mfma_f32_16x16x32_bf16 v[74:77], v[178:181], v[202:205], v[74:77]
	v_mfma_f32_16x16x32_bf16 v[70:73], v[170:173], v[210:213], v[70:73]
	v_mfma_f32_16x16x32_bf16 v[66:69], v[178:181], v[210:213], v[66:69]
	v_mfma_f32_16x16x32_bf16 v[114:117], v[174:177], v[190:193], v[114:117]
	v_mfma_f32_16x16x32_bf16 v[106:109], v[182:185], v[190:193], v[106:109]
	v_mfma_f32_16x16x32_bf16 v[98:101], v[174:177], v[198:201], v[98:101]
	v_mfma_f32_16x16x32_bf16 v[90:93], v[182:185], v[198:201], v[90:93]
	s_barrier
	v_mfma_f32_16x16x32_bf16 v[82:85], v[174:177], v[206:209], v[82:85]
	v_mfma_f32_16x16x32_bf16 v[74:77], v[182:185], v[206:209], v[74:77]
	v_mfma_f32_16x16x32_bf16 v[70:73], v[174:177], v[214:217], v[70:73]
	v_mfma_f32_16x16x32_bf16 v[66:69], v[182:185], v[214:217], v[66:69]
	s_setprio 0
	s_add_i32 s48, s70, s51
	v_lshl_add_u64 v[218:219], v[218:219], 0, s[28:29]
	s_mov_b32 m0, s48
	ds_read_b128 v[186:189], v156 offset:49152
	ds_read_b128 v[190:193], v156 offset:50176
	ds_read_b128 v[194:197], v156 offset:51200
	ds_read_b128 v[198:201], v156 offset:52224
	ds_read_b128 v[202:205], v156 offset:53248
	ds_read_b128 v[206:209], v156 offset:54272
	ds_read_b128 v[210:213], v156 offset:55296
	ds_read_b128 v[214:217], v156 offset:56320
	global_load_lds_dwordx4 v[218:219], off
	s_add_i32 m0, s48, 0x2000
	s_add_u32 s46, s46, 0x100080
	v_lshl_add_u64 v[218:219], v[220:221], 0, s[28:29]
	s_addc_u32 s47, s47, 0
	s_add_i32 s48, s71, s51
	global_load_lds_dwordx4 v[218:219], off
	v_lshl_add_u64 v[218:219], s[46:47], 0, v[134:135]
	s_mov_b32 m0, s48
	s_nop 0
	global_load_lds_dwordx4 v[218:219], off
	v_lshl_add_u64 v[218:219], s[46:47], 0, v[130:131]
	s_add_i32 m0, s48, 0x2000
	s_nop 0
	global_load_lds_dwordx4 v[218:219], off
	v_lshl_add_u64 v[218:219], v[222:223], 0, s[28:29]
	s_mov_b32 m0, s59
	s_nop 0
	global_load_lds_dwordx4 v[218:219], off
	v_lshl_add_u64 v[218:219], v[224:225], 0, s[28:29]
	s_mov_b32 m0, s60
	s_nop 0
	global_load_lds_dwordx4 v[218:219], off
	s_waitcnt vmcnt(8)
	s_waitcnt lgkmcnt(0)
	s_barrier
	s_setprio 1
	s_waitcnt lgkmcnt(0)
	v_mfma_f32_16x16x32_bf16 v[62:65], v[148:151], v[186:189], v[62:65]
	v_mfma_f32_16x16x32_bf16 v[58:61], v[162:165], v[186:189], v[58:61]
	v_mfma_f32_16x16x32_bf16 v[54:57], v[148:151], v[194:197], v[54:57]
	v_mfma_f32_16x16x32_bf16 v[46:49], v[162:165], v[194:197], v[46:49]
	v_mfma_f32_16x16x32_bf16 v[38:41], v[148:151], v[202:205], v[38:41]
	v_mfma_f32_16x16x32_bf16 v[30:33], v[162:165], v[202:205], v[30:33]
	v_mfma_f32_16x16x32_bf16 v[22:25], v[148:151], v[210:213], v[22:25]
	v_mfma_f32_16x16x32_bf16 v[14:17], v[162:165], v[210:213], v[14:17]
	v_mfma_f32_16x16x32_bf16 v[62:65], v[158:161], v[190:193], v[62:65]
	v_mfma_f32_16x16x32_bf16 v[58:61], v[166:169], v[190:193], v[58:61]
	v_mfma_f32_16x16x32_bf16 v[54:57], v[158:161], v[198:201], v[54:57]
	v_mfma_f32_16x16x32_bf16 v[46:49], v[166:169], v[198:201], v[46:49]
	v_mfma_f32_16x16x32_bf16 v[38:41], v[158:161], v[206:209], v[38:41]
	v_mfma_f32_16x16x32_bf16 v[30:33], v[166:169], v[206:209], v[30:33]
	v_mfma_f32_16x16x32_bf16 v[22:25], v[158:161], v[214:217], v[22:25]
	v_mfma_f32_16x16x32_bf16 v[14:17], v[166:169], v[214:217], v[14:17]
	s_setprio 3
	v_mfma_f32_16x16x32_bf16 v[50:53], v[170:173], v[186:189], v[50:53]
	v_mfma_f32_16x16x32_bf16 v[42:45], v[178:181], v[186:189], v[42:45]
	v_mfma_f32_16x16x32_bf16 v[34:37], v[170:173], v[194:197], v[34:37]
	v_mfma_f32_16x16x32_bf16 v[26:29], v[178:181], v[194:197], v[26:29]
	v_mfma_f32_16x16x32_bf16 v[18:21], v[170:173], v[202:205], v[18:21]
	v_mfma_f32_16x16x32_bf16 v[10:13], v[178:181], v[202:205], v[10:13]
	v_mfma_f32_16x16x32_bf16 v[6:9], v[170:173], v[210:213], v[6:9]
	v_mfma_f32_16x16x32_bf16 v[2:5], v[178:181], v[210:213], v[2:5]
	v_mfma_f32_16x16x32_bf16 v[50:53], v[174:177], v[190:193], v[50:53]
	v_mfma_f32_16x16x32_bf16 v[42:45], v[182:185], v[190:193], v[42:45]
	v_mfma_f32_16x16x32_bf16 v[34:37], v[174:177], v[198:201], v[34:37]
	v_mfma_f32_16x16x32_bf16 v[26:29], v[182:185], v[198:201], v[26:29]
	s_barrier
	v_mfma_f32_16x16x32_bf16 v[18:21], v[174:177], v[206:209], v[18:21]
	v_mfma_f32_16x16x32_bf16 v[10:13], v[182:185], v[206:209], v[10:13]
	v_mfma_f32_16x16x32_bf16 v[6:9], v[174:177], v[214:217], v[6:9]
	v_mfma_f32_16x16x32_bf16 v[2:5], v[182:185], v[214:217], v[2:5]
	s_setprio 0
	s_add_i32 s69, s69, 2
	s_add_u32 s44, s44, 0x100
	s_addc_u32 s45, s45, 0
	s_add_u32 s67, s67, 0x100
	s_addc_u32 s68, s68, 0
	s_cmp_gt_u32 s69, 61
	s_cbranch_scc0 .LBB0_115
	s_and_b64 vcc, exec, s[30:31]
	s_cbranch_vccz .LBB0_118
	s_barrier

.LBB0_540:
	v_add_u32_e32 v139, s64, v186
	ds_read_b128 v[130:133], v139
	ds_read_b128 v[134:137], v139 offset:1024
	ds_read_b128 v[146:149], v139 offset:2048
	ds_read_b128 v[150:153], v139 offset:3072
	v_add_u32_e32 v139, s65, v186
	s_add_u32 s48, s44, s46
	ds_read_b128 v[154:157], v139
	ds_read_b128 v[174:177], v139 offset:1024
	ds_read_b128 v[178:181], v139 offset:2048
	ds_read_b128 v[182:185], v139 offset:3072
	s_addc_u32 s49, s45, s47
	s_add_u32 s48, s48, 0x100
	s_addc_u32 s49, s49, 0
	s_add_u32 s71, s68, s46
	s_addc_u32 s72, s69, s47
	s_cmpk_eq_i32 s46, 0x1f00
	s_cselect_b32 s51, s39, s49
	s_cselect_b32 s50, s66, s48
	s_cselect_b32 s49, s37, s72
	s_cselect_b32 s48, s67, s71
	v_lshl_add_u64 v[222:223], v[142:143], 0, s[46:47]
	s_add_i32 m0, s55, 0xc000
	ds_read_b128 v[190:193], v188
	ds_read_b128 v[194:197], v188 offset:1024
	ds_read_b128 v[198:201], v188 offset:2048
	ds_read_b128 v[202:205], v188 offset:3072
	ds_read_b128 v[206:209], v188 offset:4096
	ds_read_b128 v[210:213], v188 offset:5120
	ds_read_b128 v[214:217], v188 offset:6144
	ds_read_b128 v[218:221], v188 offset:7168
	global_load_lds_dwordx4 v[222:223], off
	v_lshl_add_u64 v[222:223], v[144:145], 0, s[46:47]
	s_add_i32 m0, s55, 0xe000
	s_nop 0
	global_load_lds_dwordx4 v[222:223], off
	s_waitcnt vmcnt(8)
	s_waitcnt lgkmcnt(0)
	s_barrier
	s_setprio 1
	s_waitcnt lgkmcnt(0)
	v_mfma_f32_16x16x32_bf16 v[126:129], v[130:133], v[190:193], v[126:129]
	v_mfma_f32_16x16x32_bf16 v[122:125], v[146:149], v[190:193], v[122:125]
	v_mfma_f32_16x16x32_bf16 v[114:117], v[130:133], v[198:201], v[114:117]
	v_mfma_f32_16x16x32_bf16 v[106:109], v[146:149], v[198:201], v[106:109]
	v_mfma_f32_16x16x32_bf16 v[98:101], v[130:133], v[206:209], v[98:101]
	v_mfma_f32_16x16x32_bf16 v[90:93], v[146:149], v[206:209], v[90:93]
	v_mfma_f32_16x16x32_bf16 v[82:85], v[130:133], v[214:217], v[82:85]
	v_mfma_f32_16x16x32_bf16 v[74:77], v[146:149], v[214:217], v[74:77]
	v_mfma_f32_16x16x32_bf16 v[126:129], v[134:137], v[194:197], v[126:129]
	v_mfma_f32_16x16x32_bf16 v[122:125], v[150:153], v[194:197], v[122:125]
	v_mfma_f32_16x16x32_bf16 v[114:117], v[134:137], v[202:205], v[114:117]
	v_mfma_f32_16x16x32_bf16 v[106:109], v[150:153], v[202:205], v[106:109]
	v_mfma_f32_16x16x32_bf16 v[98:101], v[134:137], v[210:213], v[98:101]
	v_mfma_f32_16x16x32_bf16 v[90:93], v[150:153], v[210:213], v[90:93]
	v_mfma_f32_16x16x32_bf16 v[82:85], v[134:137], v[218:221], v[82:85]
	v_mfma_f32_16x16x32_bf16 v[74:77], v[150:153], v[218:221], v[74:77]
	s_setprio 3
	v_mfma_f32_16x16x32_bf16 v[118:121], v[154:157], v[190:193], v[118:121]
	v_mfma_f32_16x16x32_bf16 v[110:113], v[178:181], v[190:193], v[110:113]
	v_mfma_f32_16x16x32_bf16 v[102:105], v[154:157], v[198:201], v[102:105]
	v_mfma_f32_16x16x32_bf16 v[94:97], v[178:181], v[198:201], v[94:97]
	v_mfma_f32_16x16x32_bf16 v[86:89], v[154:157], v[206:209], v[86:89]
	v_mfma_f32_16x16x32_bf16 v[78:81], v[178:181], v[206:209], v[78:81]
	v_mfma_f32_16x16x32_bf16 v[70:73], v[154:157], v[214:217], v[70:73]
	v_mfma_f32_16x16x32_bf16 v[66:69], v[178:181], v[214:217], v[66:69]
	v_mfma_f32_16x16x32_bf16 v[118:121], v[174:177], v[194:197], v[118:121]
	v_mfma_f32_16x16x32_bf16 v[110:113], v[182:185], v[194:197], v[110:113]
	v_mfma_f32_16x16x32_bf16 v[102:105], v[174:177], v[202:205], v[102:105]
	v_mfma_f32_16x16x32_bf16 v[94:97], v[182:185], v[202:205], v[94:97]
	s_barrier
	v_mfma_f32_16x16x32_bf16 v[86:89], v[174:177], v[210:213], v[86:89]
	v_mfma_f32_16x16x32_bf16 v[78:81], v[182:185], v[210:213], v[78:81]
	v_mfma_f32_16x16x32_bf16 v[70:73], v[174:177], v[218:221], v[70:73]
	v_mfma_f32_16x16x32_bf16 v[66:69], v[182:185], v[218:221], v[66:69]
	s_setprio 0
	s_add_i32 s71, s64, s54
	v_lshl_add_u64 v[222:223], s[48:49], 0, v[160:161]
	s_mov_b32 m0, s71
	ds_read_b128 v[190:193], v188 offset:16384
	ds_read_b128 v[194:197], v188 offset:17408
	ds_read_b128 v[198:201], v188 offset:18432
	ds_read_b128 v[202:205], v188 offset:19456
	ds_read_b128 v[206:209], v188 offset:20480
	ds_read_b128 v[210:213], v188 offset:21504
	ds_read_b128 v[214:217], v188 offset:22528
	ds_read_b128 v[218:221], v188 offset:23552
	global_load_lds_dwordx4 v[222:223], off
	s_add_i32 m0, s71, 0x2000
	s_add_u32 s72, s48, 0x100000
	v_lshl_add_u64 v[224:225], s[48:49], 0, v[164:165]
	s_addc_u32 s73, s49, 0
	s_add_i32 s71, s65, s54
	global_load_lds_dwordx4 v[224:225], off
	v_lshl_add_u64 v[226:227], s[72:73], 0, v[160:161]
	s_mov_b32 m0, s71
	v_lshl_add_u64 v[228:229], s[50:51], 0, v[162:163]
	global_load_lds_dwordx4 v[226:227], off
	v_lshl_add_u64 v[226:227], s[72:73], 0, v[164:165]
	s_add_i32 m0, s71, 0x2000
	s_nop 0
	global_load_lds_dwordx4 v[226:227], off
	v_lshl_add_u64 v[226:227], s[50:51], 0, v[158:159]
	s_mov_b32 m0, s55
	s_nop 0
	global_load_lds_dwordx4 v[226:227], off
	s_mov_b32 m0, s56
	s_nop 0
	global_load_lds_dwordx4 v[228:229], off
	s_waitcnt vmcnt(8)
	s_waitcnt lgkmcnt(0)
	s_barrier
	s_setprio 1
	s_waitcnt lgkmcnt(0)
	v_mfma_f32_16x16x32_bf16 v[62:65], v[130:133], v[190:193], v[62:65]
	v_mfma_f32_16x16x32_bf16 v[58:61], v[146:149], v[190:193], v[58:61]
	v_mfma_f32_16x16x32_bf16 v[50:53], v[130:133], v[198:201], v[50:53]
	v_mfma_f32_16x16x32_bf16 v[42:45], v[146:149], v[198:201], v[42:45]
	v_mfma_f32_16x16x32_bf16 v[34:37], v[130:133], v[206:209], v[34:37]
	v_mfma_f32_16x16x32_bf16 v[26:29], v[146:149], v[206:209], v[26:29]
	v_mfma_f32_16x16x32_bf16 v[18:21], v[130:133], v[214:217], v[18:21]
	v_mfma_f32_16x16x32_bf16 v[10:13], v[146:149], v[214:217], v[10:13]
	v_mfma_f32_16x16x32_bf16 v[62:65], v[134:137], v[194:197], v[62:65]
	v_mfma_f32_16x16x32_bf16 v[58:61], v[150:153], v[194:197], v[58:61]
	v_mfma_f32_16x16x32_bf16 v[50:53], v[134:137], v[202:205], v[50:53]
	v_mfma_f32_16x16x32_bf16 v[42:45], v[150:153], v[202:205], v[42:45]
	v_mfma_f32_16x16x32_bf16 v[34:37], v[134:137], v[210:213], v[34:37]
	v_mfma_f32_16x16x32_bf16 v[26:29], v[150:153], v[210:213], v[26:29]
	v_mfma_f32_16x16x32_bf16 v[18:21], v[134:137], v[218:221], v[18:21]
	v_mfma_f32_16x16x32_bf16 v[10:13], v[150:153], v[218:221], v[10:13]
	s_setprio 3
	v_mfma_f32_16x16x32_bf16 v[54:57], v[154:157], v[190:193], v[54:57]
	v_mfma_f32_16x16x32_bf16 v[46:49], v[178:181], v[190:193], v[46:49]
	v_mfma_f32_16x16x32_bf16 v[38:41], v[154:157], v[198:201], v[38:41]
	v_mfma_f32_16x16x32_bf16 v[30:33], v[178:181], v[198:201], v[30:33]
	v_mfma_f32_16x16x32_bf16 v[22:25], v[154:157], v[206:209], v[22:25]
	v_mfma_f32_16x16x32_bf16 v[14:17], v[178:181], v[206:209], v[14:17]
	v_mfma_f32_16x16x32_bf16 v[6:9], v[154:157], v[214:217], v[6:9]
	v_mfma_f32_16x16x32_bf16 v[2:5], v[178:181], v[214:217], v[2:5]
	v_mfma_f32_16x16x32_bf16 v[54:57], v[174:177], v[194:197], v[54:57]
	v_mfma_f32_16x16x32_bf16 v[46:49], v[182:185], v[194:197], v[46:49]
	v_mfma_f32_16x16x32_bf16 v[38:41], v[174:177], v[202:205], v[38:41]
	v_mfma_f32_16x16x32_bf16 v[30:33], v[182:185], v[202:205], v[30:33]
	s_barrier
	v_mfma_f32_16x16x32_bf16 v[22:25], v[174:177], v[210:213], v[22:25]
	v_mfma_f32_16x16x32_bf16 v[14:17], v[182:185], v[210:213], v[14:17]
	v_mfma_f32_16x16x32_bf16 v[6:9], v[174:177], v[218:221], v[6:9]
	v_mfma_f32_16x16x32_bf16 v[2:5], v[182:185], v[218:221], v[2:5]
	s_setprio 0
	s_add_i32 s71, 0, 0x18000
	v_add_u32_e32 v139, s71, v186
	s_add_i32 s72, 0, 0x1c000
	ds_read_b128 v[130:133], v139
	ds_read_b128 v[134:137], v139 offset:1024
	ds_read_b128 v[146:149], v139 offset:2048
	ds_read_b128 v[150:153], v139 offset:3072
	v_add_u32_e32 v139, s72, v186
	ds_read_b128 v[154:157], v139
	ds_read_b128 v[174:177], v139 offset:1024
	ds_read_b128 v[178:181], v139 offset:2048
	ds_read_b128 v[182:185], v139 offset:3072
	s_add_u32 s50, s50, 0x100000
	s_addc_u32 s51, s51, 0
	s_mov_b32 m0, s57
	v_lshl_add_u64 v[230:231], s[50:51], 0, v[158:159]
	ds_read_b128 v[190:193], v188 offset:32768
	ds_read_b128 v[194:197], v188 offset:33792
	ds_read_b128 v[198:201], v188 offset:34816
	ds_read_b128 v[202:205], v188 offset:35840
	ds_read_b128 v[206:209], v188 offset:36864
	ds_read_b128 v[210:213], v188 offset:37888
	ds_read_b128 v[214:217], v188 offset:38912
	ds_read_b128 v[218:221], v188 offset:39936
	global_load_lds_dwordx4 v[230:231], off
	v_lshl_add_u64 v[230:231], s[50:51], 0, v[162:163]
	s_mov_b32 m0, s58
	s_nop 0
	global_load_lds_dwordx4 v[230:231], off
	s_waitcnt vmcnt(8)
	s_waitcnt lgkmcnt(0)
	s_barrier
	s_setprio 1
	s_waitcnt lgkmcnt(0)
	v_mfma_f32_16x16x32_bf16 v[126:129], v[130:133], v[190:193], v[126:129]
	v_mfma_f32_16x16x32_bf16 v[122:125], v[146:149], v[190:193], v[122:125]
	v_mfma_f32_16x16x32_bf16 v[114:117], v[130:133], v[198:201], v[114:117]
	v_mfma_f32_16x16x32_bf16 v[106:109], v[146:149], v[198:201], v[106:109]
	v_mfma_f32_16x16x32_bf16 v[98:101], v[130:133], v[206:209], v[98:101]
	v_mfma_f32_16x16x32_bf16 v[90:93], v[146:149], v[206:209], v[90:93]
	v_mfma_f32_16x16x32_bf16 v[82:85], v[130:133], v[214:217], v[82:85]
	v_mfma_f32_16x16x32_bf16 v[74:77], v[146:149], v[214:217], v[74:77]
	v_mfma_f32_16x16x32_bf16 v[126:129], v[134:137], v[194:197], v[126:129]
	v_mfma_f32_16x16x32_bf16 v[122:125], v[150:153], v[194:197], v[122:125]
	v_mfma_f32_16x16x32_bf16 v[114:117], v[134:137], v[202:205], v[114:117]
	v_mfma_f32_16x16x32_bf16 v[106:109], v[150:153], v[202:205], v[106:109]
	v_mfma_f32_16x16x32_bf16 v[98:101], v[134:137], v[210:213], v[98:101]
	v_mfma_f32_16x16x32_bf16 v[90:93], v[150:153], v[210:213], v[90:93]
	v_mfma_f32_16x16x32_bf16 v[82:85], v[134:137], v[218:221], v[82:85]
	v_mfma_f32_16x16x32_bf16 v[74:77], v[150:153], v[218:221], v[74:77]
	s_setprio 3
	v_mfma_f32_16x16x32_bf16 v[118:121], v[154:157], v[190:193], v[118:121]
	v_mfma_f32_16x16x32_bf16 v[110:113], v[178:181], v[190:193], v[110:113]
	v_mfma_f32_16x16x32_bf16 v[102:105], v[154:157], v[198:201], v[102:105]
	v_mfma_f32_16x16x32_bf16 v[94:97], v[178:181], v[198:201], v[94:97]
	v_mfma_f32_16x16x32_bf16 v[86:89], v[154:157], v[206:209], v[86:89]
	v_mfma_f32_16x16x32_bf16 v[78:81], v[178:181], v[206:209], v[78:81]
	v_mfma_f32_16x16x32_bf16 v[70:73], v[154:157], v[214:217], v[70:73]
	v_mfma_f32_16x16x32_bf16 v[66:69], v[178:181], v[214:217], v[66:69]
	v_mfma_f32_16x16x32_bf16 v[118:121], v[174:177], v[194:197], v[118:121]
	v_mfma_f32_16x16x32_bf16 v[110:113], v[182:185], v[194:197], v[110:113]
	v_mfma_f32_16x16x32_bf16 v[102:105], v[174:177], v[202:205], v[102:105]
	v_mfma_f32_16x16x32_bf16 v[94:97], v[182:185], v[202:205], v[94:97]
	s_barrier
	v_mfma_f32_16x16x32_bf16 v[86:89], v[174:177], v[210:213], v[86:89]
	v_mfma_f32_16x16x32_bf16 v[78:81], v[182:185], v[210:213], v[78:81]
	v_mfma_f32_16x16x32_bf16 v[70:73], v[174:177], v[218:221], v[70:73]
	v_mfma_f32_16x16x32_bf16 v[66:69], v[182:185], v[218:221], v[66:69]
	s_setprio 0
	s_add_i32 s50, s71, s54
	v_lshl_add_u64 v[222:223], v[222:223], 0, s[30:31]
	s_mov_b32 m0, s50
	ds_read_b128 v[190:193], v188 offset:49152
	ds_read_b128 v[194:197], v188 offset:50176
	ds_read_b128 v[198:201], v188 offset:51200
	ds_read_b128 v[202:205], v188 offset:52224
	ds_read_b128 v[206:209], v188 offset:53248
	ds_read_b128 v[210:213], v188 offset:54272
	ds_read_b128 v[214:217], v188 offset:55296
	ds_read_b128 v[218:221], v188 offset:56320
	global_load_lds_dwordx4 v[222:223], off
	s_add_i32 m0, s50, 0x2000
	s_add_u32 s48, s48, 0x100080
	v_lshl_add_u64 v[222:223], v[224:225], 0, s[30:31]
	s_addc_u32 s49, s49, 0
	s_add_i32 s50, s72, s54
	global_load_lds_dwordx4 v[222:223], off
	v_lshl_add_u64 v[222:223], s[48:49], 0, v[160:161]
	s_mov_b32 m0, s50
	s_nop 0
	global_load_lds_dwordx4 v[222:223], off
	v_lshl_add_u64 v[222:223], s[48:49], 0, v[164:165]
	s_add_i32 m0, s50, 0x2000
	s_nop 0
	global_load_lds_dwordx4 v[222:223], off
	v_lshl_add_u64 v[222:223], v[226:227], 0, s[30:31]
	s_mov_b32 m0, s60
	s_nop 0
	global_load_lds_dwordx4 v[222:223], off
	v_lshl_add_u64 v[222:223], v[228:229], 0, s[30:31]
	s_mov_b32 m0, s61
	s_nop 0
	global_load_lds_dwordx4 v[222:223], off
	s_waitcnt vmcnt(8)
	s_waitcnt lgkmcnt(0)
	s_barrier
	s_setprio 1
	s_waitcnt lgkmcnt(0)
	v_mfma_f32_16x16x32_bf16 v[62:65], v[130:133], v[190:193], v[62:65]
	v_mfma_f32_16x16x32_bf16 v[58:61], v[146:149], v[190:193], v[58:61]
	v_mfma_f32_16x16x32_bf16 v[50:53], v[130:133], v[198:201], v[50:53]
	v_mfma_f32_16x16x32_bf16 v[42:45], v[146:149], v[198:201], v[42:45]
	v_mfma_f32_16x16x32_bf16 v[34:37], v[130:133], v[206:209], v[34:37]
	v_mfma_f32_16x16x32_bf16 v[26:29], v[146:149], v[206:209], v[26:29]
	v_mfma_f32_16x16x32_bf16 v[18:21], v[130:133], v[214:217], v[18:21]
	v_mfma_f32_16x16x32_bf16 v[10:13], v[146:149], v[214:217], v[10:13]
	v_mfma_f32_16x16x32_bf16 v[62:65], v[134:137], v[194:197], v[62:65]
	v_mfma_f32_16x16x32_bf16 v[58:61], v[150:153], v[194:197], v[58:61]
	v_mfma_f32_16x16x32_bf16 v[50:53], v[134:137], v[202:205], v[50:53]
	v_mfma_f32_16x16x32_bf16 v[42:45], v[150:153], v[202:205], v[42:45]
	v_mfma_f32_16x16x32_bf16 v[34:37], v[134:137], v[210:213], v[34:37]
	v_mfma_f32_16x16x32_bf16 v[26:29], v[150:153], v[210:213], v[26:29]
	v_mfma_f32_16x16x32_bf16 v[18:21], v[134:137], v[218:221], v[18:21]
	v_mfma_f32_16x16x32_bf16 v[10:13], v[150:153], v[218:221], v[10:13]
	s_setprio 3
	v_mfma_f32_16x16x32_bf16 v[54:57], v[154:157], v[190:193], v[54:57]
	v_mfma_f32_16x16x32_bf16 v[46:49], v[178:181], v[190:193], v[46:49]
	v_mfma_f32_16x16x32_bf16 v[38:41], v[154:157], v[198:201], v[38:41]
	v_mfma_f32_16x16x32_bf16 v[30:33], v[178:181], v[198:201], v[30:33]
	v_mfma_f32_16x16x32_bf16 v[22:25], v[154:157], v[206:209], v[22:25]
	v_mfma_f32_16x16x32_bf16 v[14:17], v[178:181], v[206:209], v[14:17]
	v_mfma_f32_16x16x32_bf16 v[6:9], v[154:157], v[214:217], v[6:9]
	v_mfma_f32_16x16x32_bf16 v[2:5], v[178:181], v[214:217], v[2:5]
	v_mfma_f32_16x16x32_bf16 v[54:57], v[174:177], v[194:197], v[54:57]
	v_mfma_f32_16x16x32_bf16 v[46:49], v[182:185], v[194:197], v[46:49]
	v_mfma_f32_16x16x32_bf16 v[38:41], v[174:177], v[202:205], v[38:41]
	v_mfma_f32_16x16x32_bf16 v[30:33], v[182:185], v[202:205], v[30:33]
	s_barrier
	v_mfma_f32_16x16x32_bf16 v[22:25], v[174:177], v[210:213], v[22:25]
	v_mfma_f32_16x16x32_bf16 v[14:17], v[182:185], v[210:213], v[14:17]
	v_mfma_f32_16x16x32_bf16 v[6:9], v[174:177], v[218:221], v[6:9]
	v_mfma_f32_16x16x32_bf16 v[2:5], v[182:185], v[218:221], v[2:5]
	s_setprio 0
	s_add_i32 s70, s70, 2
	s_add_u32 s46, s46, 0x100
	s_addc_u32 s47, s47, 0
	s_cmp_gt_u32 s70, 61
	s_cbranch_scc1 .LBB0_543

.LBB0_618:
	ds_read_b128 v[146:149], v154
	ds_read_b128 v[158:161], v154 offset:1024
	ds_read_b128 v[162:165], v154 offset:2048
	ds_read_b128 v[166:169], v154 offset:3072
	ds_read_b128 v[170:173], v155
	ds_read_b128 v[174:177], v155 offset:1024
	ds_read_b128 v[178:181], v155 offset:2048
	ds_read_b128 v[182:185], v155 offset:3072
	s_add_u32 s48, s46, 0xfff00080
	s_addc_u32 s49, s47, -1
	s_cmp_eq_u32 s68, 60
	s_cselect_b32 s51, s39, s49
	s_cselect_b32 s50, s64, s48
	s_cselect_b32 s49, s37, s67
	s_cselect_b32 s48, s65, s66
	v_lshl_add_u64 v[150:151], s[46:47], 0, v[138:139]
	s_add_i32 m0, s45, 0xc000
	ds_read_b128 v[186:189], v156
	ds_read_b128 v[190:193], v156 offset:1024
	ds_read_b128 v[194:197], v156 offset:2048
	ds_read_b128 v[198:201], v156 offset:3072
	ds_read_b128 v[202:205], v156 offset:4096
	ds_read_b128 v[206:209], v156 offset:5120
	ds_read_b128 v[210:213], v156 offset:6144
	ds_read_b128 v[214:217], v156 offset:7168
	global_load_lds_dwordx4 v[150:151], off
	v_lshl_add_u64 v[150:151], s[46:47], 0, v[140:141]
	s_add_i32 m0, s45, 0xe000
	s_nop 0
	global_load_lds_dwordx4 v[150:151], off
	s_waitcnt vmcnt(8)
	s_waitcnt lgkmcnt(0)
	s_barrier
	s_setprio 1
	s_waitcnt lgkmcnt(0)
	v_mfma_f32_16x16x32_bf16 v[126:129], v[146:149], v[186:189], v[126:129]
	v_mfma_f32_16x16x32_bf16 v[122:125], v[162:165], v[186:189], v[122:125]
	v_mfma_f32_16x16x32_bf16 v[118:121], v[146:149], v[194:197], v[118:121]
	v_mfma_f32_16x16x32_bf16 v[114:117], v[162:165], v[194:197], v[114:117]
	v_mfma_f32_16x16x32_bf16 v[102:105], v[146:149], v[202:205], v[102:105]
	v_mfma_f32_16x16x32_bf16 v[98:101], v[162:165], v[202:205], v[98:101]
	v_mfma_f32_16x16x32_bf16 v[86:89], v[146:149], v[210:213], v[86:89]
	v_mfma_f32_16x16x32_bf16 v[78:81], v[162:165], v[210:213], v[78:81]
	v_mfma_f32_16x16x32_bf16 v[126:129], v[158:161], v[190:193], v[126:129]
	v_mfma_f32_16x16x32_bf16 v[122:125], v[166:169], v[190:193], v[122:125]
	v_mfma_f32_16x16x32_bf16 v[118:121], v[158:161], v[198:201], v[118:121]
	v_mfma_f32_16x16x32_bf16 v[114:117], v[166:169], v[198:201], v[114:117]
	v_mfma_f32_16x16x32_bf16 v[102:105], v[158:161], v[206:209], v[102:105]
	v_mfma_f32_16x16x32_bf16 v[98:101], v[166:169], v[206:209], v[98:101]
	v_mfma_f32_16x16x32_bf16 v[86:89], v[158:161], v[214:217], v[86:89]
	v_mfma_f32_16x16x32_bf16 v[78:81], v[166:169], v[214:217], v[78:81]
	s_setprio 3
	v_mfma_f32_16x16x32_bf16 v[110:113], v[170:173], v[186:189], v[110:113]
	v_mfma_f32_16x16x32_bf16 v[106:109], v[178:181], v[186:189], v[106:109]
	v_mfma_f32_16x16x32_bf16 v[94:97], v[170:173], v[194:197], v[94:97]
	v_mfma_f32_16x16x32_bf16 v[90:93], v[178:181], v[194:197], v[90:93]
	v_mfma_f32_16x16x32_bf16 v[82:85], v[170:173], v[202:205], v[82:85]
	v_mfma_f32_16x16x32_bf16 v[74:77], v[178:181], v[202:205], v[74:77]
	v_mfma_f32_16x16x32_bf16 v[70:73], v[170:173], v[210:213], v[70:73]
	v_mfma_f32_16x16x32_bf16 v[66:69], v[178:181], v[210:213], v[66:69]
	v_mfma_f32_16x16x32_bf16 v[110:113], v[174:177], v[190:193], v[110:113]
	v_mfma_f32_16x16x32_bf16 v[106:109], v[182:185], v[190:193], v[106:109]
	v_mfma_f32_16x16x32_bf16 v[94:97], v[174:177], v[198:201], v[94:97]
	v_mfma_f32_16x16x32_bf16 v[90:93], v[182:185], v[198:201], v[90:93]
	s_barrier
	v_mfma_f32_16x16x32_bf16 v[82:85], v[174:177], v[206:209], v[82:85]
	v_mfma_f32_16x16x32_bf16 v[74:77], v[182:185], v[206:209], v[74:77]
	v_mfma_f32_16x16x32_bf16 v[70:73], v[174:177], v[214:217], v[70:73]
	v_mfma_f32_16x16x32_bf16 v[66:69], v[182:185], v[214:217], v[66:69]
	s_setprio 0
	s_add_i32 s69, s61, s53
	v_lshl_add_u64 v[150:151], s[48:49], 0, v[132:133]
	s_mov_b32 m0, s69
	ds_read_b128 v[186:189], v156 offset:16384
	ds_read_b128 v[190:193], v156 offset:17408
	ds_read_b128 v[194:197], v156 offset:18432
	ds_read_b128 v[198:201], v156 offset:19456
	ds_read_b128 v[202:205], v156 offset:20480
	ds_read_b128 v[206:209], v156 offset:21504
	ds_read_b128 v[210:213], v156 offset:22528
	ds_read_b128 v[214:217], v156 offset:23552
	global_load_lds_dwordx4 v[150:151], off
	s_add_i32 m0, s69, 0x2000
	s_add_u32 s70, s48, 0x100000
	v_lshl_add_u64 v[218:219], s[48:49], 0, v[136:137]
	s_addc_u32 s71, s49, 0
	s_add_i32 s69, s62, s53
	global_load_lds_dwordx4 v[218:219], off
	v_lshl_add_u64 v[220:221], s[70:71], 0, v[132:133]
	s_mov_b32 m0, s69
	v_lshl_add_u64 v[222:223], s[50:51], 0, v[134:135]
	global_load_lds_dwordx4 v[220:221], off
	v_lshl_add_u64 v[220:221], s[70:71], 0, v[136:137]
	s_add_i32 m0, s69, 0x2000
	s_nop 0
	global_load_lds_dwordx4 v[220:221], off
	v_lshl_add_u64 v[220:221], s[50:51], 0, v[130:131]
	s_mov_b32 m0, s45
	s_nop 0
	global_load_lds_dwordx4 v[220:221], off
	s_mov_b32 m0, s54
	s_nop 0
	global_load_lds_dwordx4 v[222:223], off
	s_waitcnt vmcnt(8)
	s_waitcnt lgkmcnt(0)
	s_barrier
	s_setprio 1
	s_waitcnt lgkmcnt(0)
	v_mfma_f32_16x16x32_bf16 v[62:65], v[146:149], v[186:189], v[62:65]
	v_mfma_f32_16x16x32_bf16 v[58:61], v[162:165], v[186:189], v[58:61]
	v_mfma_f32_16x16x32_bf16 v[50:53], v[146:149], v[194:197], v[50:53]
	v_mfma_f32_16x16x32_bf16 v[42:45], v[162:165], v[194:197], v[42:45]
	v_mfma_f32_16x16x32_bf16 v[38:41], v[146:149], v[202:205], v[38:41]
	v_mfma_f32_16x16x32_bf16 v[30:33], v[162:165], v[202:205], v[30:33]
	v_mfma_f32_16x16x32_bf16 v[22:25], v[146:149], v[210:213], v[22:25]
	v_mfma_f32_16x16x32_bf16 v[14:17], v[162:165], v[210:213], v[14:17]
	v_mfma_f32_16x16x32_bf16 v[62:65], v[158:161], v[190:193], v[62:65]
	v_mfma_f32_16x16x32_bf16 v[58:61], v[166:169], v[190:193], v[58:61]
	v_mfma_f32_16x16x32_bf16 v[50:53], v[158:161], v[198:201], v[50:53]
	v_mfma_f32_16x16x32_bf16 v[42:45], v[166:169], v[198:201], v[42:45]
	v_mfma_f32_16x16x32_bf16 v[38:41], v[158:161], v[206:209], v[38:41]
	v_mfma_f32_16x16x32_bf16 v[30:33], v[166:169], v[206:209], v[30:33]
	v_mfma_f32_16x16x32_bf16 v[22:25], v[158:161], v[214:217], v[22:25]
	v_mfma_f32_16x16x32_bf16 v[14:17], v[166:169], v[214:217], v[14:17]
	s_setprio 3
	v_mfma_f32_16x16x32_bf16 v[54:57], v[170:173], v[186:189], v[54:57]
	v_mfma_f32_16x16x32_bf16 v[46:49], v[178:181], v[186:189], v[46:49]
	v_mfma_f32_16x16x32_bf16 v[34:37], v[170:173], v[194:197], v[34:37]
	v_mfma_f32_16x16x32_bf16 v[26:29], v[178:181], v[194:197], v[26:29]
	v_mfma_f32_16x16x32_bf16 v[18:21], v[170:173], v[202:205], v[18:21]
	v_mfma_f32_16x16x32_bf16 v[10:13], v[178:181], v[202:205], v[10:13]
	v_mfma_f32_16x16x32_bf16 v[6:9], v[170:173], v[210:213], v[6:9]
	v_mfma_f32_16x16x32_bf16 v[2:5], v[178:181], v[210:213], v[2:5]
	v_mfma_f32_16x16x32_bf16 v[54:57], v[174:177], v[190:193], v[54:57]
	v_mfma_f32_16x16x32_bf16 v[46:49], v[182:185], v[190:193], v[46:49]
	v_mfma_f32_16x16x32_bf16 v[34:37], v[174:177], v[198:201], v[34:37]
	v_mfma_f32_16x16x32_bf16 v[26:29], v[182:185], v[198:201], v[26:29]
	s_barrier
	v_mfma_f32_16x16x32_bf16 v[18:21], v[174:177], v[206:209], v[18:21]
	v_mfma_f32_16x16x32_bf16 v[10:13], v[182:185], v[206:209], v[10:13]
	v_mfma_f32_16x16x32_bf16 v[6:9], v[174:177], v[214:217], v[6:9]
	v_mfma_f32_16x16x32_bf16 v[2:5], v[182:185], v[214:217], v[2:5]
	s_setprio 0
	s_add_i32 s69, 0, 0x18000
	v_add_u32_e32 v157, s69, v152
	s_add_i32 s70, 0, 0x1c000
	ds_read_b128 v[146:149], v157
	ds_read_b128 v[158:161], v157 offset:1024
	ds_read_b128 v[162:165], v157 offset:2048
	ds_read_b128 v[166:169], v157 offset:3072
	v_add_u32_e32 v157, s70, v152
	ds_read_b128 v[170:173], v157
	ds_read_b128 v[174:177], v157 offset:1024
	ds_read_b128 v[178:181], v157 offset:2048
	ds_read_b128 v[182:185], v157 offset:3072
	s_add_u32 s50, s50, 0x100000
	s_addc_u32 s51, s51, 0
	s_mov_b32 m0, s55
	v_lshl_add_u64 v[224:225], s[50:51], 0, v[130:131]
	ds_read_b128 v[186:189], v156 offset:32768
	ds_read_b128 v[190:193], v156 offset:33792
	ds_read_b128 v[194:197], v156 offset:34816
	ds_read_b128 v[198:201], v156 offset:35840
	ds_read_b128 v[202:205], v156 offset:36864
	ds_read_b128 v[206:209], v156 offset:37888
	ds_read_b128 v[210:213], v156 offset:38912
	ds_read_b128 v[214:217], v156 offset:39936
	global_load_lds_dwordx4 v[224:225], off
	v_lshl_add_u64 v[224:225], s[50:51], 0, v[134:135]
	s_mov_b32 m0, s56
	s_nop 0
	global_load_lds_dwordx4 v[224:225], off
	s_waitcnt vmcnt(8)
	s_waitcnt lgkmcnt(0)
	s_barrier
	s_setprio 1
	s_waitcnt lgkmcnt(0)
	v_mfma_f32_16x16x32_bf16 v[126:129], v[146:149], v[186:189], v[126:129]
	v_mfma_f32_16x16x32_bf16 v[122:125], v[162:165], v[186:189], v[122:125]
	v_mfma_f32_16x16x32_bf16 v[118:121], v[146:149], v[194:197], v[118:121]
	v_mfma_f32_16x16x32_bf16 v[114:117], v[162:165], v[194:197], v[114:117]
	v_mfma_f32_16x16x32_bf16 v[102:105], v[146:149], v[202:205], v[102:105]
	v_mfma_f32_16x16x32_bf16 v[98:101], v[162:165], v[202:205], v[98:101]
	v_mfma_f32_16x16x32_bf16 v[86:89], v[146:149], v[210:213], v[86:89]
	v_mfma_f32_16x16x32_bf16 v[78:81], v[162:165], v[210:213], v[78:81]
	v_mfma_f32_16x16x32_bf16 v[126:129], v[158:161], v[190:193], v[126:129]
	v_mfma_f32_16x16x32_bf16 v[122:125], v[166:169], v[190:193], v[122:125]
	v_mfma_f32_16x16x32_bf16 v[118:121], v[158:161], v[198:201], v[118:121]
	v_mfma_f32_16x16x32_bf16 v[114:117], v[166:169], v[198:201], v[114:117]
	v_mfma_f32_16x16x32_bf16 v[102:105], v[158:161], v[206:209], v[102:105]
	v_mfma_f32_16x16x32_bf16 v[98:101], v[166:169], v[206:209], v[98:101]
	v_mfma_f32_16x16x32_bf16 v[86:89], v[158:161], v[214:217], v[86:89]
	v_mfma_f32_16x16x32_bf16 v[78:81], v[166:169], v[214:217], v[78:81]
	s_setprio 3
	v_mfma_f32_16x16x32_bf16 v[110:113], v[170:173], v[186:189], v[110:113]
	v_mfma_f32_16x16x32_bf16 v[106:109], v[178:181], v[186:189], v[106:109]
	v_mfma_f32_16x16x32_bf16 v[94:97], v[170:173], v[194:197], v[94:97]
	v_mfma_f32_16x16x32_bf16 v[90:93], v[178:181], v[194:197], v[90:93]
	v_mfma_f32_16x16x32_bf16 v[82:85], v[170:173], v[202:205], v[82:85]
	v_mfma_f32_16x16x32_bf16 v[74:77], v[178:181], v[202:205], v[74:77]
	v_mfma_f32_16x16x32_bf16 v[70:73], v[170:173], v[210:213], v[70:73]
	v_mfma_f32_16x16x32_bf16 v[66:69], v[178:181], v[210:213], v[66:69]
	v_mfma_f32_16x16x32_bf16 v[110:113], v[174:177], v[190:193], v[110:113]
	v_mfma_f32_16x16x32_bf16 v[106:109], v[182:185], v[190:193], v[106:109]
	v_mfma_f32_16x16x32_bf16 v[94:97], v[174:177], v[198:201], v[94:97]
	v_mfma_f32_16x16x32_bf16 v[90:93], v[182:185], v[198:201], v[90:93]
	s_barrier
	v_mfma_f32_16x16x32_bf16 v[82:85], v[174:177], v[206:209], v[82:85]
	v_mfma_f32_16x16x32_bf16 v[74:77], v[182:185], v[206:209], v[74:77]
	v_mfma_f32_16x16x32_bf16 v[70:73], v[174:177], v[214:217], v[70:73]
	v_mfma_f32_16x16x32_bf16 v[66:69], v[182:185], v[214:217], v[66:69]
	s_setprio 0
	s_add_i32 s50, s69, s53
	v_lshl_add_u64 v[150:151], v[150:151], 0, s[28:29]
	s_mov_b32 m0, s50
	ds_read_b128 v[186:189], v156 offset:49152
	ds_read_b128 v[190:193], v156 offset:50176
	ds_read_b128 v[194:197], v156 offset:51200
	ds_read_b128 v[198:201], v156 offset:52224
	ds_read_b128 v[202:205], v156 offset:53248
	ds_read_b128 v[206:209], v156 offset:54272
	ds_read_b128 v[210:213], v156 offset:55296
	ds_read_b128 v[214:217], v156 offset:56320
	global_load_lds_dwordx4 v[150:151], off
	s_add_i32 m0, s50, 0x2000
	s_add_u32 s48, s48, 0x100080
	v_lshl_add_u64 v[150:151], v[218:219], 0, s[28:29]
	s_addc_u32 s49, s49, 0
	s_add_i32 s50, s70, s53
	global_load_lds_dwordx4 v[150:151], off
	v_lshl_add_u64 v[150:151], s[48:49], 0, v[132:133]
	s_mov_b32 m0, s50
	s_nop 0
	global_load_lds_dwordx4 v[150:151], off
	v_lshl_add_u64 v[150:151], s[48:49], 0, v[136:137]
	s_add_i32 m0, s50, 0x2000
	s_nop 0
	global_load_lds_dwordx4 v[150:151], off
	v_lshl_add_u64 v[150:151], v[220:221], 0, s[28:29]
	s_mov_b32 m0, s58
	s_nop 0
	global_load_lds_dwordx4 v[150:151], off
	v_lshl_add_u64 v[150:151], v[222:223], 0, s[28:29]
	s_mov_b32 m0, s59
	s_nop 0
	global_load_lds_dwordx4 v[150:151], off
	s_waitcnt vmcnt(8)
	s_waitcnt lgkmcnt(0)
	s_barrier
	s_setprio 1
	s_waitcnt lgkmcnt(0)
	v_mfma_f32_16x16x32_bf16 v[62:65], v[146:149], v[186:189], v[62:65]
	v_mfma_f32_16x16x32_bf16 v[58:61], v[162:165], v[186:189], v[58:61]
	v_mfma_f32_16x16x32_bf16 v[50:53], v[146:149], v[194:197], v[50:53]
	v_mfma_f32_16x16x32_bf16 v[42:45], v[162:165], v[194:197], v[42:45]
	v_mfma_f32_16x16x32_bf16 v[38:41], v[146:149], v[202:205], v[38:41]
	v_mfma_f32_16x16x32_bf16 v[30:33], v[162:165], v[202:205], v[30:33]
	v_mfma_f32_16x16x32_bf16 v[22:25], v[146:149], v[210:213], v[22:25]
	v_mfma_f32_16x16x32_bf16 v[14:17], v[162:165], v[210:213], v[14:17]
	v_mfma_f32_16x16x32_bf16 v[62:65], v[158:161], v[190:193], v[62:65]
	v_mfma_f32_16x16x32_bf16 v[58:61], v[166:169], v[190:193], v[58:61]
	v_mfma_f32_16x16x32_bf16 v[50:53], v[158:161], v[198:201], v[50:53]
	v_mfma_f32_16x16x32_bf16 v[42:45], v[166:169], v[198:201], v[42:45]
	v_mfma_f32_16x16x32_bf16 v[38:41], v[158:161], v[206:209], v[38:41]
	v_mfma_f32_16x16x32_bf16 v[30:33], v[166:169], v[206:209], v[30:33]
	v_mfma_f32_16x16x32_bf16 v[22:25], v[158:161], v[214:217], v[22:25]
	v_mfma_f32_16x16x32_bf16 v[14:17], v[166:169], v[214:217], v[14:17]
	s_setprio 3
	v_mfma_f32_16x16x32_bf16 v[54:57], v[170:173], v[186:189], v[54:57]
	v_mfma_f32_16x16x32_bf16 v[46:49], v[178:181], v[186:189], v[46:49]
	v_mfma_f32_16x16x32_bf16 v[34:37], v[170:173], v[194:197], v[34:37]
	v_mfma_f32_16x16x32_bf16 v[26:29], v[178:181], v[194:197], v[26:29]
	v_mfma_f32_16x16x32_bf16 v[18:21], v[170:173], v[202:205], v[18:21]
	v_mfma_f32_16x16x32_bf16 v[10:13], v[178:181], v[202:205], v[10:13]
	v_mfma_f32_16x16x32_bf16 v[6:9], v[170:173], v[210:213], v[6:9]
	v_mfma_f32_16x16x32_bf16 v[2:5], v[178:181], v[210:213], v[2:5]
	v_mfma_f32_16x16x32_bf16 v[54:57], v[174:177], v[190:193], v[54:57]
	v_mfma_f32_16x16x32_bf16 v[46:49], v[182:185], v[190:193], v[46:49]
	v_mfma_f32_16x16x32_bf16 v[34:37], v[174:177], v[198:201], v[34:37]
	v_mfma_f32_16x16x32_bf16 v[26:29], v[182:185], v[198:201], v[26:29]
	s_barrier
	v_mfma_f32_16x16x32_bf16 v[18:21], v[174:177], v[206:209], v[18:21]
	v_mfma_f32_16x16x32_bf16 v[10:13], v[182:185], v[206:209], v[10:13]
	v_mfma_f32_16x16x32_bf16 v[6:9], v[174:177], v[214:217], v[6:9]
	v_mfma_f32_16x16x32_bf16 v[2:5], v[182:185], v[214:217], v[2:5]
	s_setprio 0
	s_add_i32 s68, s68, 2
	s_add_u32 s46, s46, 0x100
	s_addc_u32 s47, s47, 0
	s_add_u32 s66, s66, 0x100
	s_addc_u32 s67, s67, 0
	s_cmp_gt_u32 s68, 61
	s_cbranch_scc0 .LBB0_618
	s_and_b64 vcc, exec, s[30:31]
	s_cbranch_vccz .LBB0_621
	s_barrier

.LBB0_743:
	ds_read_b128 v[130:133], v197
	ds_read_b128 v[134:137], v197 offset:1024
	ds_read_b128 v[138:141], v197 offset:2048
	ds_read_b128 v[142:145], v197 offset:3072
	ds_read_b128 v[146:149], v198
	ds_read_b128 v[150:153], v198 offset:1024
	ds_read_b128 v[154:157], v198 offset:2048
	ds_read_b128 v[158:161], v198 offset:3072
	s_add_u32 s72, s70, 0xfff00080
	s_addc_u32 s73, s71, -1
	s_cmp_eq_u32 s95, 60
	s_cselect_b32 s75, s61, s73
	s_cselect_b32 s74, s67, s72
	s_cselect_b32 s73, s59, s94
	s_cselect_b32 s72, s69, s93
	v_lshl_add_u64 v[184:185], s[70:71], 0, v[176:177]
	s_add_i32 m0, s78, 0xc000
	ds_read_b128 v[200:203], v199
	ds_read_b128 v[204:207], v199 offset:1024
	ds_read_b128 v[208:211], v199 offset:2048
	ds_read_b128 v[212:215], v199 offset:3072
	ds_read_b128 v[216:219], v199 offset:4096
	ds_read_b128 v[220:223], v199 offset:5120
	ds_read_b128 v[224:227], v199 offset:6144
	ds_read_b128 v[228:231], v199 offset:7168
	global_load_lds_dwordx4 v[184:185], off
	v_lshl_add_u64 v[184:185], s[70:71], 0, v[178:179]
	s_add_i32 m0, s78, 0xe000
	s_nop 0
	global_load_lds_dwordx4 v[184:185], off
	s_waitcnt vmcnt(8)
	s_waitcnt lgkmcnt(0)
	s_barrier
	s_setprio 1
	s_waitcnt lgkmcnt(0)
	v_mfma_f32_16x16x32_bf16 v[102:105], v[130:133], v[200:203], v[102:105]
	v_mfma_f32_16x16x32_bf16 v[98:101], v[138:141], v[200:203], v[98:101]
	v_mfma_f32_16x16x32_bf16 v[110:113], v[130:133], v[208:211], v[110:113]
	v_mfma_f32_16x16x32_bf16 v[106:109], v[138:141], v[208:211], v[106:109]
	v_mfma_f32_16x16x32_bf16 v[118:121], v[130:133], v[216:219], v[118:121]
	v_mfma_f32_16x16x32_bf16 v[114:117], v[138:141], v[216:219], v[114:117]
	v_mfma_f32_16x16x32_bf16 v[126:129], v[130:133], v[224:227], v[126:129]
	v_mfma_f32_16x16x32_bf16 v[122:125], v[138:141], v[224:227], v[122:125]
	v_mfma_f32_16x16x32_bf16 v[102:105], v[134:137], v[204:207], v[102:105]
	v_mfma_f32_16x16x32_bf16 v[98:101], v[142:145], v[204:207], v[98:101]
	v_mfma_f32_16x16x32_bf16 v[110:113], v[134:137], v[212:215], v[110:113]
	v_mfma_f32_16x16x32_bf16 v[106:109], v[142:145], v[212:215], v[106:109]
	v_mfma_f32_16x16x32_bf16 v[118:121], v[134:137], v[220:223], v[118:121]
	v_mfma_f32_16x16x32_bf16 v[114:117], v[142:145], v[220:223], v[114:117]
	v_mfma_f32_16x16x32_bf16 v[126:129], v[134:137], v[228:231], v[126:129]
	v_mfma_f32_16x16x32_bf16 v[122:125], v[142:145], v[228:231], v[122:125]
	s_setprio 3
	v_mfma_f32_16x16x32_bf16 v[38:41], v[146:149], v[200:203], v[38:41]
	v_mfma_f32_16x16x32_bf16 v[34:37], v[154:157], v[200:203], v[34:37]
	v_mfma_f32_16x16x32_bf16 v[46:49], v[146:149], v[208:211], v[46:49]
	v_mfma_f32_16x16x32_bf16 v[42:45], v[154:157], v[208:211], v[42:45]
	v_mfma_f32_16x16x32_bf16 v[54:57], v[146:149], v[216:219], v[54:57]
	v_mfma_f32_16x16x32_bf16 v[50:53], v[154:157], v[216:219], v[50:53]
	v_mfma_f32_16x16x32_bf16 v[62:65], v[146:149], v[224:227], v[62:65]
	v_mfma_f32_16x16x32_bf16 v[58:61], v[154:157], v[224:227], v[58:61]
	v_mfma_f32_16x16x32_bf16 v[38:41], v[150:153], v[204:207], v[38:41]
	v_mfma_f32_16x16x32_bf16 v[34:37], v[158:161], v[204:207], v[34:37]
	v_mfma_f32_16x16x32_bf16 v[46:49], v[150:153], v[212:215], v[46:49]
	v_mfma_f32_16x16x32_bf16 v[42:45], v[158:161], v[212:215], v[42:45]
	s_barrier
	v_mfma_f32_16x16x32_bf16 v[54:57], v[150:153], v[220:223], v[54:57]
	v_mfma_f32_16x16x32_bf16 v[50:53], v[158:161], v[220:223], v[50:53]
	v_mfma_f32_16x16x32_bf16 v[62:65], v[150:153], v[228:231], v[62:65]
	v_mfma_f32_16x16x32_bf16 v[58:61], v[158:161], v[228:231], v[58:61]
	s_setprio 0
	s_add_i32 s96, s90, s77
	v_lshl_add_u64 v[184:185], s[72:73], 0, v[164:165]
	s_mov_b32 m0, s96
	ds_read_b128 v[200:203], v199 offset:16384
	ds_read_b128 v[204:207], v199 offset:17408
	ds_read_b128 v[208:211], v199 offset:18432
	ds_read_b128 v[212:215], v199 offset:19456
	ds_read_b128 v[216:219], v199 offset:20480
	ds_read_b128 v[220:223], v199 offset:21504
	ds_read_b128 v[224:227], v199 offset:22528
	ds_read_b128 v[228:231], v199 offset:23552
	global_load_lds_dwordx4 v[184:185], off
	s_add_i32 m0, s96, 0x2000
	s_add_u32 s96, s72, 0x100000
	v_lshl_add_u64 v[232:233], s[72:73], 0, v[168:169]
	s_addc_u32 s97, s73, 0
	s_add_i32 vcc_lo, s91, s77
	global_load_lds_dwordx4 v[232:233], off
	v_lshl_add_u64 v[234:235], s[96:97], 0, v[164:165]
	s_mov_b32 m0, vcc_lo
	v_lshl_add_u64 v[236:237], s[74:75], 0, v[166:167]
	global_load_lds_dwordx4 v[234:235], off
	v_lshl_add_u64 v[234:235], s[96:97], 0, v[168:169]
	s_add_i32 m0, vcc_lo, 0x2000
	s_nop 0
	global_load_lds_dwordx4 v[234:235], off
	v_lshl_add_u64 v[234:235], s[74:75], 0, v[162:163]
	s_mov_b32 m0, s78
	s_nop 0
	global_load_lds_dwordx4 v[234:235], off
	s_mov_b32 m0, s79
	s_nop 0
	global_load_lds_dwordx4 v[236:237], off
	s_waitcnt vmcnt(8)
	s_waitcnt lgkmcnt(0)
	s_barrier
	s_setprio 1
	s_waitcnt lgkmcnt(0)
	v_mfma_f32_16x16x32_bf16 v[70:73], v[130:133], v[200:203], v[70:73]
	v_mfma_f32_16x16x32_bf16 v[66:69], v[138:141], v[200:203], v[66:69]
	v_mfma_f32_16x16x32_bf16 v[78:81], v[130:133], v[208:211], v[78:81]
	v_mfma_f32_16x16x32_bf16 v[74:77], v[138:141], v[208:211], v[74:77]
	v_mfma_f32_16x16x32_bf16 v[86:89], v[130:133], v[216:219], v[86:89]
	v_mfma_f32_16x16x32_bf16 v[82:85], v[138:141], v[216:219], v[82:85]
	v_mfma_f32_16x16x32_bf16 v[94:97], v[130:133], v[224:227], v[94:97]
	v_mfma_f32_16x16x32_bf16 v[90:93], v[138:141], v[224:227], v[90:93]
	v_mfma_f32_16x16x32_bf16 v[70:73], v[134:137], v[204:207], v[70:73]
	v_mfma_f32_16x16x32_bf16 v[66:69], v[142:145], v[204:207], v[66:69]
	v_mfma_f32_16x16x32_bf16 v[78:81], v[134:137], v[212:215], v[78:81]
	v_mfma_f32_16x16x32_bf16 v[74:77], v[142:145], v[212:215], v[74:77]
	v_mfma_f32_16x16x32_bf16 v[86:89], v[134:137], v[220:223], v[86:89]
	v_mfma_f32_16x16x32_bf16 v[82:85], v[142:145], v[220:223], v[82:85]
	v_mfma_f32_16x16x32_bf16 v[94:97], v[134:137], v[228:231], v[94:97]
	v_mfma_f32_16x16x32_bf16 v[90:93], v[142:145], v[228:231], v[90:93]
	s_setprio 3
	v_mfma_f32_16x16x32_bf16 v[6:9], v[146:149], v[200:203], v[6:9]
	v_mfma_f32_16x16x32_bf16 v[2:5], v[154:157], v[200:203], v[2:5]
	v_mfma_f32_16x16x32_bf16 v[14:17], v[146:149], v[208:211], v[14:17]
	v_mfma_f32_16x16x32_bf16 v[10:13], v[154:157], v[208:211], v[10:13]
	v_mfma_f32_16x16x32_bf16 v[22:25], v[146:149], v[216:219], v[22:25]
	v_mfma_f32_16x16x32_bf16 v[18:21], v[154:157], v[216:219], v[18:21]
	v_mfma_f32_16x16x32_bf16 v[30:33], v[146:149], v[224:227], v[30:33]
	v_mfma_f32_16x16x32_bf16 v[26:29], v[154:157], v[224:227], v[26:29]
	v_mfma_f32_16x16x32_bf16 v[6:9], v[150:153], v[204:207], v[6:9]
	v_mfma_f32_16x16x32_bf16 v[2:5], v[158:161], v[204:207], v[2:5]
	v_mfma_f32_16x16x32_bf16 v[14:17], v[150:153], v[212:215], v[14:17]
	v_mfma_f32_16x16x32_bf16 v[10:13], v[158:161], v[212:215], v[10:13]
	s_barrier
	v_mfma_f32_16x16x32_bf16 v[22:25], v[150:153], v[220:223], v[22:25]
	v_mfma_f32_16x16x32_bf16 v[18:21], v[158:161], v[220:223], v[18:21]
	v_mfma_f32_16x16x32_bf16 v[30:33], v[150:153], v[228:231], v[30:33]
	v_mfma_f32_16x16x32_bf16 v[26:29], v[158:161], v[228:231], v[26:29]
	s_setprio 0
	s_add_i32 s96, 0, 0x18000
	s_add_i32 s97, 0, 0x1c000
	v_add_u32_e32 v142, s96, v173
	v_add_u32_e32 v158, s97, v173
	ds_read_b128 v[130:133], v142
	ds_read_b128 v[134:137], v142 offset:1024
	ds_read_b128 v[138:141], v142 offset:2048
	ds_read_b128 v[142:145], v142 offset:3072
	ds_read_b128 v[146:149], v158
	ds_read_b128 v[150:153], v158 offset:1024
	ds_read_b128 v[154:157], v158 offset:2048
	ds_read_b128 v[158:161], v158 offset:3072
	s_add_u32 s74, s74, 0x100000
	s_addc_u32 s75, s75, 0
	s_mov_b32 m0, s80
	v_lshl_add_u64 v[238:239], s[74:75], 0, v[162:163]
	ds_read_b128 v[200:203], v199 offset:32768
	ds_read_b128 v[204:207], v199 offset:33792
	ds_read_b128 v[208:211], v199 offset:34816
	ds_read_b128 v[212:215], v199 offset:35840
	ds_read_b128 v[216:219], v199 offset:36864
	ds_read_b128 v[220:223], v199 offset:37888
	ds_read_b128 v[224:227], v199 offset:38912
	ds_read_b128 v[228:231], v199 offset:39936
	global_load_lds_dwordx4 v[238:239], off
	v_lshl_add_u64 v[238:239], s[74:75], 0, v[166:167]
	s_mov_b32 m0, s81
	s_nop 0
	global_load_lds_dwordx4 v[238:239], off
	s_waitcnt vmcnt(8)
	s_waitcnt lgkmcnt(0)
	s_barrier
	s_setprio 1
	s_waitcnt lgkmcnt(0)
	v_mfma_f32_16x16x32_bf16 v[102:105], v[130:133], v[200:203], v[102:105]
	v_mfma_f32_16x16x32_bf16 v[98:101], v[138:141], v[200:203], v[98:101]
	v_mfma_f32_16x16x32_bf16 v[110:113], v[130:133], v[208:211], v[110:113]
	v_mfma_f32_16x16x32_bf16 v[106:109], v[138:141], v[208:211], v[106:109]
	v_mfma_f32_16x16x32_bf16 v[118:121], v[130:133], v[216:219], v[118:121]
	v_mfma_f32_16x16x32_bf16 v[114:117], v[138:141], v[216:219], v[114:117]
	v_mfma_f32_16x16x32_bf16 v[126:129], v[130:133], v[224:227], v[126:129]
	v_mfma_f32_16x16x32_bf16 v[122:125], v[138:141], v[224:227], v[122:125]
	v_mfma_f32_16x16x32_bf16 v[102:105], v[134:137], v[204:207], v[102:105]
	v_mfma_f32_16x16x32_bf16 v[98:101], v[142:145], v[204:207], v[98:101]
	v_mfma_f32_16x16x32_bf16 v[110:113], v[134:137], v[212:215], v[110:113]
	v_mfma_f32_16x16x32_bf16 v[106:109], v[142:145], v[212:215], v[106:109]
	v_mfma_f32_16x16x32_bf16 v[118:121], v[134:137], v[220:223], v[118:121]
	v_mfma_f32_16x16x32_bf16 v[114:117], v[142:145], v[220:223], v[114:117]
	v_mfma_f32_16x16x32_bf16 v[126:129], v[134:137], v[228:231], v[126:129]
	v_mfma_f32_16x16x32_bf16 v[122:125], v[142:145], v[228:231], v[122:125]
	s_setprio 3
	v_mfma_f32_16x16x32_bf16 v[38:41], v[146:149], v[200:203], v[38:41]
	v_mfma_f32_16x16x32_bf16 v[34:37], v[154:157], v[200:203], v[34:37]
	v_mfma_f32_16x16x32_bf16 v[46:49], v[146:149], v[208:211], v[46:49]
	v_mfma_f32_16x16x32_bf16 v[42:45], v[154:157], v[208:211], v[42:45]
	v_mfma_f32_16x16x32_bf16 v[54:57], v[146:149], v[216:219], v[54:57]
	v_mfma_f32_16x16x32_bf16 v[50:53], v[154:157], v[216:219], v[50:53]
	v_mfma_f32_16x16x32_bf16 v[62:65], v[146:149], v[224:227], v[62:65]
	v_mfma_f32_16x16x32_bf16 v[58:61], v[154:157], v[224:227], v[58:61]
	v_mfma_f32_16x16x32_bf16 v[38:41], v[150:153], v[204:207], v[38:41]
	v_mfma_f32_16x16x32_bf16 v[34:37], v[158:161], v[204:207], v[34:37]
	v_mfma_f32_16x16x32_bf16 v[46:49], v[150:153], v[212:215], v[46:49]
	v_mfma_f32_16x16x32_bf16 v[42:45], v[158:161], v[212:215], v[42:45]
	s_barrier
	v_mfma_f32_16x16x32_bf16 v[54:57], v[150:153], v[220:223], v[54:57]
	v_mfma_f32_16x16x32_bf16 v[50:53], v[158:161], v[220:223], v[50:53]
	v_mfma_f32_16x16x32_bf16 v[62:65], v[150:153], v[228:231], v[62:65]
	v_mfma_f32_16x16x32_bf16 v[58:61], v[158:161], v[228:231], v[58:61]
	s_setprio 0
	s_add_i32 s74, s96, s77
	v_lshl_add_u64 v[184:185], v[184:185], 0, s[38:39]
	s_mov_b32 m0, s74
	ds_read_b128 v[200:203], v199 offset:49152
	ds_read_b128 v[204:207], v199 offset:50176
	ds_read_b128 v[208:211], v199 offset:51200
	ds_read_b128 v[212:215], v199 offset:52224
	ds_read_b128 v[216:219], v199 offset:53248
	ds_read_b128 v[220:223], v199 offset:54272
	ds_read_b128 v[224:227], v199 offset:55296
	ds_read_b128 v[228:231], v199 offset:56320
	global_load_lds_dwordx4 v[184:185], off
	s_add_i32 m0, s74, 0x2000
	s_add_u32 s72, s72, 0x100080
	v_lshl_add_u64 v[184:185], v[232:233], 0, s[38:39]
	s_addc_u32 s73, s73, 0
	s_add_i32 s74, s97, s77
	global_load_lds_dwordx4 v[184:185], off
	v_lshl_add_u64 v[184:185], s[72:73], 0, v[164:165]
	s_mov_b32 m0, s74
	s_nop 0
	global_load_lds_dwordx4 v[184:185], off
	v_lshl_add_u64 v[184:185], s[72:73], 0, v[168:169]
	s_add_i32 m0, s74, 0x2000
	s_nop 0
	global_load_lds_dwordx4 v[184:185], off
	v_lshl_add_u64 v[184:185], v[234:235], 0, s[38:39]
	s_mov_b32 m0, s85
	s_nop 0
	global_load_lds_dwordx4 v[184:185], off
	v_lshl_add_u64 v[184:185], v[236:237], 0, s[38:39]
	s_mov_b32 m0, s86
	s_nop 0
	global_load_lds_dwordx4 v[184:185], off
	s_waitcnt vmcnt(8)
	s_waitcnt lgkmcnt(0)
	s_barrier
	s_setprio 1
	s_waitcnt lgkmcnt(0)
	v_mfma_f32_16x16x32_bf16 v[70:73], v[130:133], v[200:203], v[70:73]
	v_mfma_f32_16x16x32_bf16 v[66:69], v[138:141], v[200:203], v[66:69]
	v_mfma_f32_16x16x32_bf16 v[78:81], v[130:133], v[208:211], v[78:81]
	v_mfma_f32_16x16x32_bf16 v[74:77], v[138:141], v[208:211], v[74:77]
	v_mfma_f32_16x16x32_bf16 v[86:89], v[130:133], v[216:219], v[86:89]
	v_mfma_f32_16x16x32_bf16 v[82:85], v[138:141], v[216:219], v[82:85]
	v_mfma_f32_16x16x32_bf16 v[94:97], v[130:133], v[224:227], v[94:97]
	v_mfma_f32_16x16x32_bf16 v[90:93], v[138:141], v[224:227], v[90:93]
	v_mfma_f32_16x16x32_bf16 v[70:73], v[134:137], v[204:207], v[70:73]
	v_mfma_f32_16x16x32_bf16 v[66:69], v[142:145], v[204:207], v[66:69]
	v_mfma_f32_16x16x32_bf16 v[78:81], v[134:137], v[212:215], v[78:81]
	v_mfma_f32_16x16x32_bf16 v[74:77], v[142:145], v[212:215], v[74:77]
	v_mfma_f32_16x16x32_bf16 v[86:89], v[134:137], v[220:223], v[86:89]
	v_mfma_f32_16x16x32_bf16 v[82:85], v[142:145], v[220:223], v[82:85]
	v_mfma_f32_16x16x32_bf16 v[94:97], v[134:137], v[228:231], v[94:97]
	v_mfma_f32_16x16x32_bf16 v[90:93], v[142:145], v[228:231], v[90:93]
	s_setprio 3
	v_mfma_f32_16x16x32_bf16 v[6:9], v[146:149], v[200:203], v[6:9]
	v_mfma_f32_16x16x32_bf16 v[2:5], v[154:157], v[200:203], v[2:5]
	v_mfma_f32_16x16x32_bf16 v[14:17], v[146:149], v[208:211], v[14:17]
	v_mfma_f32_16x16x32_bf16 v[10:13], v[154:157], v[208:211], v[10:13]
	v_mfma_f32_16x16x32_bf16 v[22:25], v[146:149], v[216:219], v[22:25]
	v_mfma_f32_16x16x32_bf16 v[18:21], v[154:157], v[216:219], v[18:21]
	v_mfma_f32_16x16x32_bf16 v[30:33], v[146:149], v[224:227], v[30:33]
	v_mfma_f32_16x16x32_bf16 v[26:29], v[154:157], v[224:227], v[26:29]
	v_mfma_f32_16x16x32_bf16 v[6:9], v[150:153], v[204:207], v[6:9]
	v_mfma_f32_16x16x32_bf16 v[2:5], v[158:161], v[204:207], v[2:5]
	v_mfma_f32_16x16x32_bf16 v[14:17], v[150:153], v[212:215], v[14:17]
	v_mfma_f32_16x16x32_bf16 v[10:13], v[158:161], v[212:215], v[10:13]
	s_barrier
	v_mfma_f32_16x16x32_bf16 v[22:25], v[150:153], v[220:223], v[22:25]
	v_mfma_f32_16x16x32_bf16 v[18:21], v[158:161], v[220:223], v[18:21]
	v_mfma_f32_16x16x32_bf16 v[30:33], v[150:153], v[228:231], v[30:33]
	v_mfma_f32_16x16x32_bf16 v[26:29], v[158:161], v[228:231], v[26:29]
	s_setprio 0
	s_add_i32 s95, s95, 2
	s_add_u32 s70, s70, 0x100
	s_addc_u32 s71, s71, 0
	s_add_u32 s93, s93, 0x100
	s_addc_u32 s94, s94, 0
	s_cmp_gt_u32 s95, 61
	s_cbranch_scc0 .LBB0_743
	s_and_b64 vcc, exec, s[40:41]
	s_cbranch_vccz .LBB0_746
	s_barrier

.LBB0_902:
	ds_read_b128 v[144:147], v155
	ds_read_b128 v[148:151], v155 offset:1024
	ds_read_b128 v[158:161], v155 offset:2048
	ds_read_b128 v[162:165], v155 offset:3072
	ds_read_b128 v[166:169], v156
	ds_read_b128 v[170:173], v156 offset:1024
	ds_read_b128 v[174:177], v156 offset:2048
	ds_read_b128 v[178:181], v156 offset:3072
	s_add_u32 s50, s48, 0x100
	s_addc_u32 s51, s49, 0
	s_cmpk_eq_i32 s73, 0xa8
	s_cselect_b32 s55, s9, s51
	s_cselect_b32 s54, s8, s50
	s_cselect_b32 s53, s47, s72
	s_cselect_b32 s52, s46, s71
	v_lshl_add_u64 v[214:215], s[48:49], 0, v[136:137]
	s_add_i32 m0, s57, 0xc000
	ds_read_b128 v[182:185], v157
	ds_read_b128 v[186:189], v157 offset:1024
	ds_read_b128 v[190:193], v157 offset:2048
	ds_read_b128 v[194:197], v157 offset:3072
	ds_read_b128 v[198:201], v157 offset:4096
	ds_read_b128 v[202:205], v157 offset:5120
	ds_read_b128 v[206:209], v157 offset:6144
	ds_read_b128 v[210:213], v157 offset:7168
	global_load_lds_dwordx4 v[214:215], off
	v_lshl_add_u64 v[214:215], s[48:49], 0, v[138:139]
	s_add_i32 m0, s57, 0xe000
	s_nop 0
	global_load_lds_dwordx4 v[214:215], off
	s_waitcnt vmcnt(8)
	s_waitcnt lgkmcnt(0)
	s_barrier
	s_setprio 1
	s_waitcnt lgkmcnt(0)
	v_mfma_f32_16x16x32_bf16 v[124:127], v[144:147], v[182:185], v[124:127]
	v_mfma_f32_16x16x32_bf16 v[120:123], v[158:161], v[182:185], v[120:123]
	v_mfma_f32_16x16x32_bf16 v[116:119], v[144:147], v[190:193], v[116:119]
	v_mfma_f32_16x16x32_bf16 v[112:115], v[158:161], v[190:193], v[112:115]
	v_mfma_f32_16x16x32_bf16 v[92:95], v[144:147], v[198:201], v[92:95]
	v_mfma_f32_16x16x32_bf16 v[88:91], v[158:161], v[198:201], v[88:91]
	v_mfma_f32_16x16x32_bf16 v[76:79], v[144:147], v[206:209], v[76:79]
	v_mfma_f32_16x16x32_bf16 v[72:75], v[158:161], v[206:209], v[72:75]
	v_mfma_f32_16x16x32_bf16 v[124:127], v[148:151], v[186:189], v[124:127]
	v_mfma_f32_16x16x32_bf16 v[120:123], v[162:165], v[186:189], v[120:123]
	v_mfma_f32_16x16x32_bf16 v[116:119], v[148:151], v[194:197], v[116:119]
	v_mfma_f32_16x16x32_bf16 v[112:115], v[162:165], v[194:197], v[112:115]
	v_mfma_f32_16x16x32_bf16 v[92:95], v[148:151], v[202:205], v[92:95]
	v_mfma_f32_16x16x32_bf16 v[88:91], v[162:165], v[202:205], v[88:91]
	v_mfma_f32_16x16x32_bf16 v[76:79], v[148:151], v[210:213], v[76:79]
	v_mfma_f32_16x16x32_bf16 v[72:75], v[162:165], v[210:213], v[72:75]
	s_setprio 3
	v_mfma_f32_16x16x32_bf16 v[108:111], v[166:169], v[182:185], v[108:111]
	v_mfma_f32_16x16x32_bf16 v[104:107], v[174:177], v[182:185], v[104:107]
	v_mfma_f32_16x16x32_bf16 v[100:103], v[166:169], v[190:193], v[100:103]
	v_mfma_f32_16x16x32_bf16 v[96:99], v[174:177], v[190:193], v[96:99]
	v_mfma_f32_16x16x32_bf16 v[84:87], v[166:169], v[198:201], v[84:87]
	v_mfma_f32_16x16x32_bf16 v[80:83], v[174:177], v[198:201], v[80:83]
	v_mfma_f32_16x16x32_bf16 v[68:71], v[166:169], v[206:209], v[68:71]
	v_mfma_f32_16x16x32_bf16 v[64:67], v[174:177], v[206:209], v[64:67]
	v_mfma_f32_16x16x32_bf16 v[108:111], v[170:173], v[186:189], v[108:111]
	v_mfma_f32_16x16x32_bf16 v[104:107], v[178:181], v[186:189], v[104:107]
	v_mfma_f32_16x16x32_bf16 v[100:103], v[170:173], v[194:197], v[100:103]
	v_mfma_f32_16x16x32_bf16 v[96:99], v[178:181], v[194:197], v[96:99]
	s_barrier
	v_mfma_f32_16x16x32_bf16 v[84:87], v[170:173], v[202:205], v[84:87]
	v_mfma_f32_16x16x32_bf16 v[80:83], v[178:181], v[202:205], v[80:83]
	v_mfma_f32_16x16x32_bf16 v[68:71], v[170:173], v[210:213], v[68:71]
	v_mfma_f32_16x16x32_bf16 v[64:67], v[178:181], v[210:213], v[64:67]
	s_setprio 0
	s_add_i32 s48, s65, s56
	v_lshl_add_u64 v[214:215], s[52:53], 0, v[130:131]
	s_mov_b32 m0, s48
	ds_read_b128 v[182:185], v157 offset:16384
	ds_read_b128 v[186:189], v157 offset:17408
	ds_read_b128 v[190:193], v157 offset:18432
	ds_read_b128 v[194:197], v157 offset:19456
	ds_read_b128 v[198:201], v157 offset:20480
	ds_read_b128 v[202:205], v157 offset:21504
	ds_read_b128 v[206:209], v157 offset:22528
	ds_read_b128 v[210:213], v157 offset:23552
	global_load_lds_dwordx4 v[214:215], off
	s_add_i32 m0, s48, 0x2000
	s_add_u32 s48, s52, 0x2b0000
	v_lshl_add_u64 v[216:217], s[52:53], 0, v[134:135]
	s_addc_u32 s49, s53, 0
	s_add_i32 s74, s66, s56
	global_load_lds_dwordx4 v[216:217], off
	v_lshl_add_u64 v[218:219], s[48:49], 0, v[130:131]
	s_mov_b32 m0, s74
	v_lshl_add_u64 v[220:221], s[54:55], 0, v[132:133]
	global_load_lds_dwordx4 v[218:219], off
	v_lshl_add_u64 v[218:219], s[48:49], 0, v[134:135]
	s_add_i32 m0, s74, 0x2000
	s_nop 0
	global_load_lds_dwordx4 v[218:219], off
	v_lshl_add_u64 v[218:219], s[54:55], 0, v[128:129]
	s_mov_b32 m0, s57
	s_nop 0
	global_load_lds_dwordx4 v[218:219], off
	s_mov_b32 m0, s58
	s_nop 0
	global_load_lds_dwordx4 v[220:221], off
	s_waitcnt vmcnt(8)
	s_waitcnt lgkmcnt(0)
	s_barrier
	s_setprio 1
	s_waitcnt lgkmcnt(0)
	v_mfma_f32_16x16x32_bf16 v[60:63], v[144:147], v[182:185], v[60:63]
	v_mfma_f32_16x16x32_bf16 v[56:59], v[158:161], v[182:185], v[56:59]
	v_mfma_f32_16x16x32_bf16 v[44:47], v[144:147], v[190:193], v[44:47]
	v_mfma_f32_16x16x32_bf16 v[40:43], v[158:161], v[190:193], v[40:43]
	v_mfma_f32_16x16x32_bf16 v[28:31], v[144:147], v[198:201], v[28:31]
	v_mfma_f32_16x16x32_bf16 v[24:27], v[158:161], v[198:201], v[24:27]
	v_mfma_f32_16x16x32_bf16 v[12:15], v[144:147], v[206:209], v[12:15]
	v_mfma_f32_16x16x32_bf16 v[8:11], v[158:161], v[206:209], v[8:11]
	v_mfma_f32_16x16x32_bf16 v[60:63], v[148:151], v[186:189], v[60:63]
	v_mfma_f32_16x16x32_bf16 v[56:59], v[162:165], v[186:189], v[56:59]
	v_mfma_f32_16x16x32_bf16 v[44:47], v[148:151], v[194:197], v[44:47]
	v_mfma_f32_16x16x32_bf16 v[40:43], v[162:165], v[194:197], v[40:43]
	v_mfma_f32_16x16x32_bf16 v[28:31], v[148:151], v[202:205], v[28:31]
	v_mfma_f32_16x16x32_bf16 v[24:27], v[162:165], v[202:205], v[24:27]
	v_mfma_f32_16x16x32_bf16 v[12:15], v[148:151], v[210:213], v[12:15]
	v_mfma_f32_16x16x32_bf16 v[8:11], v[162:165], v[210:213], v[8:11]
	s_setprio 3
	v_mfma_f32_16x16x32_bf16 v[52:55], v[166:169], v[182:185], v[52:55]
	v_mfma_f32_16x16x32_bf16 v[48:51], v[174:177], v[182:185], v[48:51]
	v_mfma_f32_16x16x32_bf16 v[36:39], v[166:169], v[190:193], v[36:39]
	v_mfma_f32_16x16x32_bf16 v[32:35], v[174:177], v[190:193], v[32:35]
	v_mfma_f32_16x16x32_bf16 v[20:23], v[166:169], v[198:201], v[20:23]
	v_mfma_f32_16x16x32_bf16 v[16:19], v[174:177], v[198:201], v[16:19]
	v_mfma_f32_16x16x32_bf16 v[4:7], v[166:169], v[206:209], v[4:7]
	v_mfma_f32_16x16x32_bf16 v[0:3], v[174:177], v[206:209], v[0:3]
	v_mfma_f32_16x16x32_bf16 v[52:55], v[170:173], v[186:189], v[52:55]
	v_mfma_f32_16x16x32_bf16 v[48:51], v[178:181], v[186:189], v[48:51]
	v_mfma_f32_16x16x32_bf16 v[36:39], v[170:173], v[194:197], v[36:39]
	v_mfma_f32_16x16x32_bf16 v[32:35], v[178:181], v[194:197], v[32:35]
	s_barrier
	v_mfma_f32_16x16x32_bf16 v[20:23], v[170:173], v[202:205], v[20:23]
	v_mfma_f32_16x16x32_bf16 v[16:19], v[178:181], v[202:205], v[16:19]
	v_mfma_f32_16x16x32_bf16 v[4:7], v[170:173], v[210:213], v[4:7]
	v_mfma_f32_16x16x32_bf16 v[0:3], v[178:181], v[210:213], v[0:3]
	s_setprio 0
	s_add_i32 s74, 0, 0x18000
	s_add_i32 s75, 0, 0x1c000
	v_add_u32_e32 v162, s74, v153
	v_add_u32_e32 v178, s75, v153
	ds_read_b128 v[144:147], v162
	ds_read_b128 v[148:151], v162 offset:1024
	ds_read_b128 v[158:161], v162 offset:2048
	ds_read_b128 v[162:165], v162 offset:3072
	ds_read_b128 v[166:169], v178
	ds_read_b128 v[170:173], v178 offset:1024
	ds_read_b128 v[174:177], v178 offset:2048
	ds_read_b128 v[178:181], v178 offset:3072
	s_add_u32 s48, s54, 0x2b0000
	s_addc_u32 s49, s55, 0
	s_mov_b32 m0, s59
	v_lshl_add_u64 v[222:223], s[48:49], 0, v[128:129]
	ds_read_b128 v[182:185], v157 offset:32768
	ds_read_b128 v[186:189], v157 offset:33792
	ds_read_b128 v[190:193], v157 offset:34816
	ds_read_b128 v[194:197], v157 offset:35840
	ds_read_b128 v[198:201], v157 offset:36864
	ds_read_b128 v[202:205], v157 offset:37888
	ds_read_b128 v[206:209], v157 offset:38912
	ds_read_b128 v[210:213], v157 offset:39936
	global_load_lds_dwordx4 v[222:223], off
	v_lshl_add_u64 v[222:223], s[48:49], 0, v[132:133]
	s_mov_b32 m0, s60
	s_nop 0
	global_load_lds_dwordx4 v[222:223], off
	s_waitcnt vmcnt(8)
	s_waitcnt lgkmcnt(0)
	s_barrier
	s_setprio 1
	s_waitcnt lgkmcnt(0)
	v_mfma_f32_16x16x32_bf16 v[124:127], v[144:147], v[182:185], v[124:127]
	v_mfma_f32_16x16x32_bf16 v[120:123], v[158:161], v[182:185], v[120:123]
	v_mfma_f32_16x16x32_bf16 v[116:119], v[144:147], v[190:193], v[116:119]
	v_mfma_f32_16x16x32_bf16 v[112:115], v[158:161], v[190:193], v[112:115]
	v_mfma_f32_16x16x32_bf16 v[92:95], v[144:147], v[198:201], v[92:95]
	v_mfma_f32_16x16x32_bf16 v[88:91], v[158:161], v[198:201], v[88:91]
	v_mfma_f32_16x16x32_bf16 v[76:79], v[144:147], v[206:209], v[76:79]
	v_mfma_f32_16x16x32_bf16 v[72:75], v[158:161], v[206:209], v[72:75]
	v_mfma_f32_16x16x32_bf16 v[124:127], v[148:151], v[186:189], v[124:127]
	v_mfma_f32_16x16x32_bf16 v[120:123], v[162:165], v[186:189], v[120:123]
	v_mfma_f32_16x16x32_bf16 v[116:119], v[148:151], v[194:197], v[116:119]
	v_mfma_f32_16x16x32_bf16 v[112:115], v[162:165], v[194:197], v[112:115]
	v_mfma_f32_16x16x32_bf16 v[92:95], v[148:151], v[202:205], v[92:95]
	v_mfma_f32_16x16x32_bf16 v[88:91], v[162:165], v[202:205], v[88:91]
	v_mfma_f32_16x16x32_bf16 v[76:79], v[148:151], v[210:213], v[76:79]
	v_mfma_f32_16x16x32_bf16 v[72:75], v[162:165], v[210:213], v[72:75]
	s_setprio 3
	v_mfma_f32_16x16x32_bf16 v[108:111], v[166:169], v[182:185], v[108:111]
	v_mfma_f32_16x16x32_bf16 v[104:107], v[174:177], v[182:185], v[104:107]
	v_mfma_f32_16x16x32_bf16 v[100:103], v[166:169], v[190:193], v[100:103]
	v_mfma_f32_16x16x32_bf16 v[96:99], v[174:177], v[190:193], v[96:99]
	v_mfma_f32_16x16x32_bf16 v[84:87], v[166:169], v[198:201], v[84:87]
	v_mfma_f32_16x16x32_bf16 v[80:83], v[174:177], v[198:201], v[80:83]
	v_mfma_f32_16x16x32_bf16 v[68:71], v[166:169], v[206:209], v[68:71]
	v_mfma_f32_16x16x32_bf16 v[64:67], v[174:177], v[206:209], v[64:67]
	v_mfma_f32_16x16x32_bf16 v[108:111], v[170:173], v[186:189], v[108:111]
	v_mfma_f32_16x16x32_bf16 v[104:107], v[178:181], v[186:189], v[104:107]
	v_mfma_f32_16x16x32_bf16 v[100:103], v[170:173], v[194:197], v[100:103]
	v_mfma_f32_16x16x32_bf16 v[96:99], v[178:181], v[194:197], v[96:99]
	s_barrier
	v_mfma_f32_16x16x32_bf16 v[84:87], v[170:173], v[202:205], v[84:87]
	v_mfma_f32_16x16x32_bf16 v[80:83], v[178:181], v[202:205], v[80:83]
	v_mfma_f32_16x16x32_bf16 v[68:71], v[170:173], v[210:213], v[68:71]
	v_mfma_f32_16x16x32_bf16 v[64:67], v[178:181], v[210:213], v[64:67]
	s_setprio 0
	s_add_i32 s48, s74, s56
	v_lshl_add_u64 v[214:215], v[214:215], 0, s[30:31]
	s_mov_b32 m0, s48
	ds_read_b128 v[182:185], v157 offset:49152
	ds_read_b128 v[186:189], v157 offset:50176
	ds_read_b128 v[190:193], v157 offset:51200
	ds_read_b128 v[194:197], v157 offset:52224
	ds_read_b128 v[198:201], v157 offset:53248
	ds_read_b128 v[202:205], v157 offset:54272
	ds_read_b128 v[206:209], v157 offset:55296
	ds_read_b128 v[210:213], v157 offset:56320
	global_load_lds_dwordx4 v[214:215], off
	s_add_i32 m0, s48, 0x2000
	s_add_u32 s48, s52, 0x2b0080
	v_lshl_add_u64 v[214:215], v[216:217], 0, s[30:31]
	s_addc_u32 s49, s53, 0
	s_add_i32 s52, s75, s56
	global_load_lds_dwordx4 v[214:215], off
	v_lshl_add_u64 v[214:215], s[48:49], 0, v[130:131]
	s_mov_b32 m0, s52
	s_nop 0
	global_load_lds_dwordx4 v[214:215], off
	v_lshl_add_u64 v[214:215], s[48:49], 0, v[134:135]
	s_add_i32 m0, s52, 0x2000
	s_nop 0
	global_load_lds_dwordx4 v[214:215], off
	v_lshl_add_u64 v[214:215], v[218:219], 0, s[30:31]
	s_mov_b32 m0, s62
	s_nop 0
	global_load_lds_dwordx4 v[214:215], off
	v_lshl_add_u64 v[214:215], v[220:221], 0, s[30:31]
	s_mov_b32 m0, s63
	s_nop 0
	global_load_lds_dwordx4 v[214:215], off
	s_waitcnt vmcnt(8)
	s_waitcnt lgkmcnt(0)
	s_barrier
	s_setprio 1
	s_waitcnt lgkmcnt(0)
	v_mfma_f32_16x16x32_bf16 v[60:63], v[144:147], v[182:185], v[60:63]
	v_mfma_f32_16x16x32_bf16 v[56:59], v[158:161], v[182:185], v[56:59]
	v_mfma_f32_16x16x32_bf16 v[44:47], v[144:147], v[190:193], v[44:47]
	v_mfma_f32_16x16x32_bf16 v[40:43], v[158:161], v[190:193], v[40:43]
	v_mfma_f32_16x16x32_bf16 v[28:31], v[144:147], v[198:201], v[28:31]
	v_mfma_f32_16x16x32_bf16 v[24:27], v[158:161], v[198:201], v[24:27]
	v_mfma_f32_16x16x32_bf16 v[12:15], v[144:147], v[206:209], v[12:15]
	v_mfma_f32_16x16x32_bf16 v[8:11], v[158:161], v[206:209], v[8:11]
	v_mfma_f32_16x16x32_bf16 v[60:63], v[148:151], v[186:189], v[60:63]
	v_mfma_f32_16x16x32_bf16 v[56:59], v[162:165], v[186:189], v[56:59]
	v_mfma_f32_16x16x32_bf16 v[44:47], v[148:151], v[194:197], v[44:47]
	v_mfma_f32_16x16x32_bf16 v[40:43], v[162:165], v[194:197], v[40:43]
	v_mfma_f32_16x16x32_bf16 v[28:31], v[148:151], v[202:205], v[28:31]
	v_mfma_f32_16x16x32_bf16 v[24:27], v[162:165], v[202:205], v[24:27]
	v_mfma_f32_16x16x32_bf16 v[12:15], v[148:151], v[210:213], v[12:15]
	v_mfma_f32_16x16x32_bf16 v[8:11], v[162:165], v[210:213], v[8:11]
	s_setprio 3
	v_mfma_f32_16x16x32_bf16 v[52:55], v[166:169], v[182:185], v[52:55]
	v_mfma_f32_16x16x32_bf16 v[48:51], v[174:177], v[182:185], v[48:51]
	v_mfma_f32_16x16x32_bf16 v[36:39], v[166:169], v[190:193], v[36:39]
	v_mfma_f32_16x16x32_bf16 v[32:35], v[174:177], v[190:193], v[32:35]
	v_mfma_f32_16x16x32_bf16 v[20:23], v[166:169], v[198:201], v[20:23]
	v_mfma_f32_16x16x32_bf16 v[16:19], v[174:177], v[198:201], v[16:19]
	v_mfma_f32_16x16x32_bf16 v[4:7], v[166:169], v[206:209], v[4:7]
	v_mfma_f32_16x16x32_bf16 v[0:3], v[174:177], v[206:209], v[0:3]
	v_mfma_f32_16x16x32_bf16 v[52:55], v[170:173], v[186:189], v[52:55]
	v_mfma_f32_16x16x32_bf16 v[48:51], v[178:181], v[186:189], v[48:51]
	v_mfma_f32_16x16x32_bf16 v[36:39], v[170:173], v[194:197], v[36:39]
	v_mfma_f32_16x16x32_bf16 v[32:35], v[178:181], v[194:197], v[32:35]
	s_barrier
	v_mfma_f32_16x16x32_bf16 v[20:23], v[170:173], v[202:205], v[20:23]
	v_mfma_f32_16x16x32_bf16 v[16:19], v[178:181], v[202:205], v[16:19]
	v_mfma_f32_16x16x32_bf16 v[4:7], v[170:173], v[210:213], v[4:7]
	v_mfma_f32_16x16x32_bf16 v[0:3], v[178:181], v[210:213], v[0:3]
	s_setprio 0
	s_add_i32 s73, s73, 2
	s_add_u32 s71, s71, 0x100
	s_addc_u32 s72, s72, 0
	s_cmpk_gt_u32 s73, 0xa9
	s_mov_b64 s[48:49], s[50:51]
	s_cbranch_scc0 .LBB0_902
	s_and_b64 vcc, exec, s[34:35]
	s_cbranch_vccz .LBB0_905
	s_barrier
